# drop the f32 h round trip: P9 recomputes LN1(alpha*x+mix) in registers (hand-written fused LN1+LN2 row loop), P5 stops storing f32 h, P8 writes bf16 ffn to the dead hb region so mix survives; same num
# speedup vs baseline: 1.0209x; 1.0047x over previous
; __device__ __forceinline__ unsigned cvtpk(float lo, float hi) { f32x2_t v = {lo, hi}; bf16x2_t b = __builtin_convertvector(v, bf16x2_t); return __builtin_bit_cast(unsigned, b); }
; #define PHASE_IDS() int tid_p = threadIdx.x; asm volatile("" : "+v"(tid_p)); const int lane = tid_p & 63; const int wave_p = __builtin_amdgcn_readfirstlane(tid_p >> 6); \
;     const int gw = vcu * NWAVES + wave_p, NGW = G * NWAVES; const size_t gt = (size_t)bx * NTHREADS + tid_p, NGT = (size_t)G * NTHREADS; (void)lane; (void)gw; (void)NGW; (void)gt; (void)NGT
; __global__ void __launch_bounds__(NTHREADS, 2) fwd_megakernel(Args args) {
;     ...
;     { PHASE_IDS();
;     for (int m = gw; m < MTOK; m += NGW) {
;         float* row = HF + (size_t)m * DM; const float* xr = x + (size_t)m * DM; const bf16* mr = MIXB + (size_t)m * DM; f32x4 v[8]; float s = 0.f;
; #pragma unroll
;         for (int j = 0; j < 8; ++j) { const int c = 4 * (lane + 64 * j); const f32x4 xv = __builtin_nontemporal_load((const f32x4*)(xr + c)); const v2u mv = *(const v2u*)(mr + c);
;             v[j] = xv * ALPHA + (f32x4){bflo(mv.x), bfhi(mv.x), bflo(mv.y), bfhi(mv.y)}; s += (v[j][0] + v[j][1]) + (v[j][2] + v[j][3]); }
;         const float mean = wave_sum(s) * (1.f / DM); float s2 = 0.f;
; #pragma unroll
;         for (int j = 0; j < 8; ++j) { v[j] = v[j] - mean; s2 += (v[j][0] * v[j][0] + v[j][1] * v[j][1]) + (v[j][2] * v[j][2] + v[j][3] * v[j][3]); }
;         const float rstd = 1.f / sqrtf(wave_sum(s2) * (1.f / DM) + LN_EPS);
; #pragma unroll
;         for (int j = 0; j < 8; ++j) { const int c = 4 * (lane + 64 * j); const f32x4 gg = *(const f32x4*)(ln1_g + c), bb = *(const f32x4*)(ln1_b + c);
;             const f32x4 o = v[j] * rstd * gg + bb; *(f32x4*)(row + c) = o;
;             v2u wv; wv.x = cvtpk(o[0], o[1]); wv.y = cvtpk(o[2], o[3]); *(v2u*)(HB + (size_t)m * DM + c) = wv; }
.LBB0_340:
	s_or_b64 exec, exec, s[4:5]
	s_waitcnt lgkmcnt(0)
	v_mov_b32_e32 v0, v178
	s_barrier
	v_writelane_b32 v244, s12, 16
	v_writelane_b32 v244, s13, 17
	v_writelane_b32 v244, s20, 18
	v_writelane_b32 v244, s21, 19
	v_writelane_b32 v244, s22, 20
	v_writelane_b32 v244, s23, 21
	v_mbcnt_lo_u32_b32 v179, -1, 0
	v_readfirstlane_b32 s0, v0
	s_ashr_i32 s4, s0, 6
	s_add_i32 s0, s4, s89
	s_cmpk_gt_i32 s0, 0x7fff
	s_cbranch_scc1 .LBB0_343
	v_mbcnt_hi_u32_b32 v1, -1, v179
	v_and_b32_e32 v2, 64, v1
	v_add_u32_e32 v2, 64, v2
	v_xor_b32_e32 v3, 1, v1
	v_cmp_lt_i32_e32 vcc, v3, v2
	s_ashr_i32 s5, s4, 31
	s_ashr_i32 s6, s89, 31
	v_cndmask_b32_e32 v3, v1, v3, vcc
	v_lshlrev_b32_e32 v54, 2, v3
	v_xor_b32_e32 v3, 2, v1
	v_cmp_lt_i32_e32 vcc, v3, v2
	s_add_u32 s4, s4, s89
	s_addc_u32 s5, s5, s6
	v_cndmask_b32_e32 v3, v1, v3, vcc
	v_lshlrev_b32_e32 v55, 2, v3
	v_xor_b32_e32 v3, 4, v1
	v_cmp_lt_i32_e32 vcc, v3, v2
	s_lshl_b64 s[6:7], s[4:5], 12
	s_ashr_i32 s29, s28, 31
	v_cndmask_b32_e32 v3, v1, v3, vcc
	v_lshlrev_b32_e32 v56, 2, v3
	v_xor_b32_e32 v3, 8, v1
	v_cmp_lt_i32_e32 vcc, v3, v2
	s_lshl_b64 s[4:5], s[4:5], 13
	s_movk_i32 s1, 0x1000
	v_cndmask_b32_e32 v3, v1, v3, vcc
	v_lshlrev_b32_e32 v57, 2, v3
	v_xor_b32_e32 v3, 16, v1
	v_cmp_lt_i32_e32 vcc, v3, v2
	v_mov_b32_e32 v29, s7
	v_mov_b32_e32 v31, s5
	v_cndmask_b32_e32 v3, v1, v3, vcc
	v_lshlrev_b32_e32 v58, 2, v3
	v_xor_b32_e32 v3, 32, v1
	v_cmp_lt_i32_e32 vcc, v3, v2
	s_lshl_b64 s[8:9], s[28:29], 13
	s_mov_b32 s10, 0x3f9837f0
	v_cndmask_b32_e32 v1, v1, v3, vcc
	v_lshlrev_b32_e32 v59, 2, v1
	v_lshlrev_b32_e32 v1, 4, v0
	v_and_b32_e32 v2, 0x3f0, v1
	v_mov_b32_e32 v3, 0
	v_or_b32_e32 v4, 0x1000, v2
	v_mov_b32_e32 v5, v3
	v_lshl_add_u64 v[12:13], s[20:21], 0, v[4:5]
	v_lshl_add_u64 v[14:15], s[22:23], 0, v[4:5]
	v_or_b32_e32 v4, 0x1400, v2
	v_lshl_add_u64 v[8:9], s[20:21], 0, v[2:3]
	v_lshl_add_u64 v[10:11], s[22:23], 0, v[2:3]
	v_lshl_add_u64 v[16:17], s[20:21], 0, v[4:5]
	v_lshl_add_u64 v[18:19], s[22:23], 0, v[4:5]
	v_or_b32_e32 v4, 0x1800, v2
	v_or_b32_e32 v2, 0x1c00, v2
	v_and_b32_e32 v0, 63, v0
	v_lshl_add_u64 v[20:21], s[20:21], 0, v[4:5]
	v_lshl_add_u64 v[22:23], s[22:23], 0, v[4:5]
	v_lshl_add_u64 v[24:25], s[20:21], 0, v[2:3]
	v_lshl_add_u64 v[26:27], s[22:23], 0, v[2:3]
	v_lshl_or_b32 v28, v0, 3, s6
	s_lshl_b64 s[6:7], s[28:29], 12
	v_lshl_or_b32 v30, v0, 4, s4
	v_mov_b32_e32 v60, 0x3727c5ac
	s_mov_b32 s11, 0xf800000
	v_mov_b32_e32 v61, 0x260
	s_mov_b32 s20, 0x17c00000
	s_mov_b32 s21, 0x7c00000
	s_mov_b32 s22, 0x17c01000
	global_load_dwordx4 v[114:117], v[8:9], off
	global_load_dwordx4 v[118:121], v[10:11], off
	global_load_dwordx4 v[122:125], v[8:9], off offset:1024
	global_load_dwordx4 v[126:129], v[10:11], off offset:1024
	global_load_dwordx4 v[130:133], v[8:9], off offset:2048
	global_load_dwordx4 v[134:137], v[10:11], off offset:2048
	global_load_dwordx4 v[138:141], v[8:9], off offset:3072
	global_load_dwordx4 v[142:145], v[10:11], off offset:3072
	global_load_dwordx4 v[146:149], v[12:13], off
	global_load_dwordx4 v[150:153], v[14:15], off
	global_load_dwordx4 v[154:157], v[12:13], off offset:1024
	global_load_dwordx4 v[158:161], v[14:15], off offset:1024
	global_load_dwordx4 v[162:165], v[12:13], off offset:2048
	global_load_dwordx4 v[166:169], v[14:15], off offset:2048
	global_load_dwordx4 v[170:173], v[12:13], off offset:3072
	global_load_dwordx4 v[174:177], v[14:15], off offset:3072
	s_waitcnt vmcnt(0)
.LBB0_342:
	v_lshl_add_u64 v[32:33], s[12:13], 0, v[30:31]
	v_add_co_u32_e64 v78, s[4:5], s1, v32
	v_lshl_add_u64 v[48:49], s[40:41], 0, v[30:31]
	s_nop 0
	v_addc_co_u32_e64 v79, s[4:5], 0, v33, s[4:5]
	v_lshl_add_u64 v[36:37], s[40:41], 0, v[28:29]
	global_load_dwordx4 v[38:41], v[32:33], off nt
	global_load_dwordx4 v[42:45], v[32:33], off offset:1024 nt
	global_load_dwordx4 v[50:53], v[32:33], off offset:2048 nt
	global_load_dwordx4 v[62:65], v[32:33], off offset:3072 nt
	v_add_co_u32_e64 v32, s[4:5], s22, v48
	v_add_co_u32_e32 v46, vcc, 0xfc00000, v36
	s_nop 0
	v_addc_co_u32_e64 v33, s[4:5], 0, v49, s[4:5]
	v_add_co_u32_e64 v34, s[4:5], s21, v36
	v_addc_co_u32_e32 v47, vcc, 0, v37, vcc
	s_nop 0
	v_addc_co_u32_e64 v35, s[4:5], 0, v37, s[4:5]
	global_load_dwordx4 v[66:69], v[78:79], off nt
	global_load_dwordx4 v[70:73], v[78:79], off offset:1024 nt
	global_load_dwordx4 v[74:77], v[78:79], off offset:2048 nt
	s_nop 0
	global_load_dwordx4 v[78:81], v[78:79], off offset:3072 nt
	s_nop 0
	global_load_dwordx2 v[36:37], v[46:47], off
	global_load_dwordx2 v[82:83], v[46:47], off offset:512
	global_load_dwordx2 v[84:85], v[46:47], off offset:1024
	global_load_dwordx2 v[86:87], v[46:47], off offset:1536
	global_load_dwordx2 v[88:89], v[46:47], off offset:2048
	global_load_dwordx2 v[90:91], v[46:47], off offset:2560
	global_load_dwordx2 v[92:93], v[46:47], off offset:3072
	s_nop 0
	global_load_dwordx2 v[46:47], v[46:47], off offset:3584
	s_add_i32 s0, s0, s28
	v_lshl_add_u64 v[28:29], v[28:29], 0, s[6:7]
	v_lshl_add_u64 v[30:31], v[30:31], 0, s[8:9]
	s_cmpk_gt_i32 s0, 0x7fff
	s_waitcnt vmcnt(7)
	v_lshlrev_b32_e32 v94, 16, v36
	v_and_b32_e32 v95, 0xffff0000, v36
	v_lshlrev_b32_e32 v36, 16, v37
	v_and_b32_e32 v37, 0xffff0000, v37
	s_waitcnt vmcnt(6)
	v_lshlrev_b32_e32 v96, 16, v82
	v_and_b32_e32 v97, 0xffff0000, v82
	v_lshlrev_b32_e32 v82, 16, v83
	v_and_b32_e32 v83, 0xffff0000, v83
	s_waitcnt vmcnt(5)
	v_lshlrev_b32_e32 v98, 16, v84
	v_and_b32_e32 v99, 0xffff0000, v84
	v_lshlrev_b32_e32 v84, 16, v85
	v_and_b32_e32 v85, 0xffff0000, v85
	s_waitcnt vmcnt(3)
	v_lshlrev_b32_e32 v102, 16, v88
	v_and_b32_e32 v103, 0xffff0000, v88
	v_lshlrev_b32_e32 v88, 16, v89
	v_and_b32_e32 v89, 0xffff0000, v89
	s_waitcnt vmcnt(2)
; __global__ void __launch_bounds__(NTHREADS, 2) fwd_megakernel(Args args) {
;     ...
;         float* row = HF + (size_t)m * DM; const float* xr = x + (size_t)m * DM; const bf16* mr = MIXB + (size_t)m * DM; f32x4 v[8]; float s = 0.f;
; #pragma unroll
;         for (int j = 0; j < 8; ++j) { const int c = 4 * (lane + 64 * j); const f32x4 xv = __builtin_nontemporal_load((const f32x4*)(xr + c)); const v2u mv = *(const v2u*)(mr + c);
;             v[j] = xv * ALPHA + (f32x4){bflo(mv.x), bfhi(mv.x), bflo(mv.y), bfhi(mv.y)}; s += (v[j][0] + v[j][1]) + (v[j][2] + v[j][3]); }
;         const float mean = wave_sum(s) * (1.f / DM); float s2 = 0.f;
; #pragma unroll
;         for (int j = 0; j < 8; ++j) { v[j] = v[j] - mean; s2 += (v[j][0] * v[j][0] + v[j][1] * v[j][1]) + (v[j][2] * v[j][2] + v[j][3] * v[j][3]); }
	v_lshlrev_b32_e32 v104, 16, v90
	v_and_b32_e32 v105, 0xffff0000, v90
	v_lshlrev_b32_e32 v90, 16, v91
	v_and_b32_e32 v91, 0xffff0000, v91
	v_pk_fma_f32 v[112:113], v[40:41], s[10:11], v[36:37] op_sel_hi:[1,0,1]
	v_pk_fma_f32 v[94:95], v[38:39], s[10:11], v[94:95] op_sel_hi:[1,0,1]
	v_pk_fma_f32 v[82:83], v[44:45], s[10:11], v[82:83] op_sel_hi:[1,0,1]
	v_pk_fma_f32 v[96:97], v[42:43], s[10:11], v[96:97] op_sel_hi:[1,0,1]
	s_waitcnt vmcnt(1)
	v_lshlrev_b32_e32 v106, 16, v92
	v_and_b32_e32 v107, 0xffff0000, v92
	v_lshlrev_b32_e32 v92, 16, v93
	v_and_b32_e32 v93, 0xffff0000, v93
	s_waitcnt vmcnt(0)
	v_lshlrev_b32_e32 v108, 16, v46
	v_and_b32_e32 v109, 0xffff0000, v46
	v_lshlrev_b32_e32 v110, 16, v47
	v_and_b32_e32 v111, 0xffff0000, v47
	v_pk_fma_f32 v[84:85], v[52:53], s[10:11], v[84:85] op_sel_hi:[1,0,1]
	v_pk_fma_f32 v[98:99], v[50:51], s[10:11], v[98:99] op_sel_hi:[1,0,1]
	v_pk_fma_f32 v[52:53], v[68:69], s[10:11], v[88:89] op_sel_hi:[1,0,1]
	v_pk_fma_f32 v[50:51], v[66:67], s[10:11], v[102:103] op_sel_hi:[1,0,1]
	v_pk_fma_f32 v[46:47], v[72:73], s[10:11], v[90:91] op_sel_hi:[1,0,1]
	v_pk_fma_f32 v[44:45], v[70:71], s[10:11], v[104:105] op_sel_hi:[1,0,1]
	v_mov_b32_e32 v66, v94
	v_mov_b32_e32 v67, v96
	v_mov_b32_e32 v68, v95
	v_mov_b32_e32 v69, v97
	v_mov_b32_e32 v70, v112
	v_mov_b32_e32 v71, v82
	v_mov_b32_e32 v72, v113
	v_mov_b32_e32 v73, v83
	v_pk_fma_f32 v[42:43], v[76:77], s[10:11], v[92:93] op_sel_hi:[1,0,1]
	v_pk_fma_f32 v[40:41], v[74:75], s[10:11], v[106:107] op_sel_hi:[1,0,1]
	v_pk_mov_b32 v[74:75], v[98:99], v[84:85] op_sel:[1,0]
	v_mov_b32_e32 v76, v98
	v_mov_b32_e32 v77, v85
	v_pk_add_f32 v[66:67], v[66:67], v[68:69]
	v_pk_add_f32 v[68:69], v[70:71], v[72:73]
	v_lshlrev_b32_e32 v100, 16, v86
	v_and_b32_e32 v101, 0xffff0000, v86
	v_lshlrev_b32_e32 v86, 16, v87
	v_and_b32_e32 v87, 0xffff0000, v87
	v_pk_add_f32 v[70:71], v[74:75], v[76:77]
	v_pk_add_f32 v[66:67], v[66:67], v[68:69]
	v_pk_fma_f32 v[64:65], v[64:65], s[10:11], v[86:87] op_sel_hi:[1,0,1]
	v_pk_fma_f32 v[62:63], v[62:63], s[10:11], v[100:101] op_sel_hi:[1,0,1]
	v_pk_add_f32 v[68:69], v[70:71], v[70:71] op_sel:[0,1] op_sel_hi:[1,0]
	v_add_f32_e32 v66, 0, v66
	v_pk_fma_f32 v[38:39], v[80:81], s[10:11], v[110:111] op_sel_hi:[1,0,1]
	v_pk_fma_f32 v[36:37], v[78:79], s[10:11], v[108:109] op_sel_hi:[1,0,1]
	v_add_f32_e32 v78, v62, v63
	v_add_f32_e32 v80, v64, v65
	v_mov_b32_e32 v87, v50
	v_mov_b32_e32 v79, v52
	v_mov_b32_e32 v81, v53
	v_mov_b32_e32 v69, v51
	v_add_f32_e32 v86, v66, v67
	v_pk_mov_b32 v[88:89], v[44:45], v[46:47] op_sel:[1,0]
	v_mov_b32_e32 v90, v44
	v_mov_b32_e32 v91, v47
	v_pk_add_f32 v[72:73], v[78:79], v[80:81]
	v_pk_add_f32 v[66:67], v[86:87], v[68:69]
	v_pk_add_f32 v[74:75], v[88:89], v[90:91]
	v_pk_add_f32 v[66:67], v[66:67], v[72:73]
	v_pk_add_f32 v[70:71], v[74:75], v[74:75] op_sel:[0,1] op_sel_hi:[1,0]
	v_pk_add_f32 v[66:67], v[66:67], v[66:67] op_sel:[0,1] op_sel_hi:[1,0]
	v_add_f32_e32 v92, v40, v41
	v_add_f32_e32 v100, v42, v43
	v_mov_b32_e32 v93, v38
	v_mov_b32_e32 v101, v39
	v_mov_b32_e32 v71, v37
	v_mov_b32_e32 v67, v36
	v_pk_add_f32 v[76:77], v[92:93], v[100:101]
	v_pk_add_f32 v[66:67], v[66:67], v[70:71]
	s_nop 0
	v_pk_add_f32 v[66:67], v[66:67], v[76:77]
	s_nop 0
	v_add_f32_e32 v66, v66, v67
	ds_bpermute_b32 v67, v54, v66
	s_waitcnt lgkmcnt(0)
	v_add_f32_e32 v66, v66, v67
	ds_bpermute_b32 v67, v55, v66
	s_waitcnt lgkmcnt(0)
	v_add_f32_e32 v66, v66, v67
	ds_bpermute_b32 v67, v56, v66
	s_waitcnt lgkmcnt(0)
	v_add_f32_e32 v66, v66, v67
	ds_bpermute_b32 v67, v57, v66
	s_waitcnt lgkmcnt(0)
	v_add_f32_e32 v66, v66, v67
	ds_bpermute_b32 v67, v58, v66
	s_waitcnt lgkmcnt(0)
	v_add_f32_e32 v66, v66, v67
	ds_bpermute_b32 v67, v59, v66
	s_waitcnt lgkmcnt(0)
	v_add_f32_e32 v66, v66, v67
	v_fmamk_f32 v113, v66, 0xba000000, v113
	v_fmamk_f32 v95, v66, 0xba000000, v95
	v_fmamk_f32 v83, v66, 0xba000000, v83
	v_fmamk_f32 v97, v66, 0xba000000, v97
	v_fmac_f32_e32 v112, 0xba000000, v66
	v_fmac_f32_e32 v94, 0xba000000, v66
	v_fmac_f32_e32 v82, 0xba000000, v66
	v_fmac_f32_e32 v96, 0xba000000, v66
	v_fmamk_f32 v99, v66, 0xba000000, v99
	v_fmac_f32_e32 v98, 0xba000000, v66
	v_fmamk_f32 v85, v66, 0xba000000, v85
	v_fmac_f32_e32 v84, 0xba000000, v66
	v_mov_b32_e32 v68, v95
	v_mov_b32_e32 v69, v97
	v_mov_b32_e32 v72, v113
	v_mov_b32_e32 v73, v83
	v_fmamk_f32 v63, v66, 0xba000000, v63
	v_fmac_f32_e32 v62, 0xba000000, v66
	v_fmamk_f32 v65, v66, 0xba000000, v65
	v_fmac_f32_e32 v64, 0xba000000, v66
	v_fmamk_f32 v53, v66, 0xba000000, v53
	v_fmac_f32_e32 v52, 0xba000000, v66
	v_fmamk_f32 v51, v66, 0xba000000, v51
	v_fmac_f32_e32 v50, 0xba000000, v66
	v_fmamk_f32 v45, v66, 0xba000000, v45
	v_fmac_f32_e32 v44, 0xba000000, v66
	v_fmamk_f32 v47, v66, 0xba000000, v47
	v_fmac_f32_e32 v46, 0xba000000, v66
	v_fmamk_f32 v41, v66, 0xba000000, v41
	v_fmac_f32_e32 v40, 0xba000000, v66
	v_fmamk_f32 v43, v66, 0xba000000, v43
	v_fmac_f32_e32 v42, 0xba000000, v66
	v_fmamk_f32 v39, v66, 0xba000000, v39
	v_fmac_f32_e32 v38, 0xba000000, v66
	v_fmamk_f32 v37, v66, 0xba000000, v37
	v_fmac_f32_e32 v36, 0xba000000, v66
	v_mov_b32_e32 v66, v94
	v_mov_b32_e32 v67, v96
	v_mov_b32_e32 v70, v112
	v_mov_b32_e32 v71, v82
	v_pk_mul_f32 v[74:75], v[84:85], v[84:85]
	v_pk_mul_f32 v[76:77], v[98:99], v[98:99]
	v_pk_mul_f32 v[68:69], v[68:69], v[68:69]
	v_pk_mul_f32 v[72:73], v[72:73], v[72:73]
	v_pk_mov_b32 v[100:101], v[76:77], v[74:75] op_sel:[1,0]
	v_mov_b32_e32 v77, v75
	v_pk_fma_f32 v[66:67], v[66:67], v[66:67], v[68:69]
	v_pk_fma_f32 v[68:69], v[70:71], v[70:71], v[72:73]
	v_mul_f32_e32 v78, v63, v63
	v_mul_f32_e32 v80, v65, v65
	v_pk_add_f32 v[70:71], v[100:101], v[76:77]
	v_pk_add_f32 v[66:67], v[66:67], v[68:69]
; __device__ __forceinline__ unsigned cvtpk(float lo, float hi) { f32x2_t v = {lo, hi}; bf16x2_t b = __builtin_convertvector(v, bf16x2_t); return __builtin_bit_cast(unsigned, b); }
; __global__ void __launch_bounds__(NTHREADS, 2) fwd_megakernel(Args args) {
;     ...
;         const float mean = wave_sum(s) * (1.f / DM); float s2 = 0.f;
; #pragma unroll
;         for (int j = 0; j < 8; ++j) { v[j] = v[j] - mean; s2 += (v[j][0] * v[j][0] + v[j][1] * v[j][1]) + (v[j][2] * v[j][2] + v[j][3] * v[j][3]); }
;         const float rstd = 1.f / sqrtf(wave_sum(s2) * (1.f / DM) + LN_EPS);
; #pragma unroll
;         for (int j = 0; j < 8; ++j) { const int c = 4 * (lane + 64 * j); const f32x4 gg = *(const f32x4*)(ln1_g + c), bb = *(const f32x4*)(ln1_b + c);
;             const f32x4 o = v[j] * rstd * gg + bb; *(f32x4*)(row + c) = o;
;             v2u wv; wv.x = cvtpk(o[0], o[1]); wv.y = cvtpk(o[2], o[3]); *(v2u*)(HB + (size_t)m * DM + c) = wv; }
	v_mul_f32_e32 v93, v50, v50
	v_mul_f32_e32 v102, v51, v51
	v_mul_f32_e32 v103, v52, v52
	v_mul_f32_e32 v104, v53, v53
	v_pk_fma_f32 v[74:75], v[62:63], v[62:63], v[78:79] op_sel_hi:[1,1,0]
	v_pk_fma_f32 v[78:79], v[64:65], v[64:65], v[80:81] op_sel_hi:[1,1,0]
	v_pk_add_f32 v[68:69], v[70:71], v[70:71] op_sel:[0,1] op_sel_hi:[1,0]
	v_pk_add_f32 v[66:67], v[66:67], v[66:67] op_sel:[0,1] op_sel_hi:[1,0]
	v_pk_mul_f32 v[86:87], v[46:47], v[46:47]
	v_pk_mul_f32 v[88:89], v[44:45], v[44:45]
	v_mov_b32_e32 v75, v103
	v_mov_b32_e32 v79, v104
	v_mov_b32_e32 v69, v102
	v_mov_b32_e32 v67, v93
	v_pk_mov_b32 v[80:81], v[88:89], v[86:87] op_sel:[1,0]
	v_mov_b32_e32 v89, v87
	v_pk_add_f32 v[70:71], v[74:75], v[78:79]
	v_pk_add_f32 v[66:67], v[66:67], v[68:69]
	v_mul_f32_e32 v90, v41, v41
	v_mul_f32_e32 v92, v43, v43
	v_pk_add_f32 v[72:73], v[80:81], v[88:89]
	v_pk_add_f32 v[66:67], v[66:67], v[70:71]
	v_mul_f32_e32 v105, v36, v36
	v_mul_f32_e32 v106, v37, v37
	v_mul_f32_e32 v107, v38, v38
	v_mul_f32_e32 v108, v39, v39
	v_pk_fma_f32 v[86:87], v[40:41], v[40:41], v[90:91] op_sel_hi:[1,1,0]
	v_pk_fma_f32 v[90:91], v[42:43], v[42:43], v[92:93] op_sel_hi:[1,1,0]
	v_pk_add_f32 v[72:73], v[72:73], v[72:73] op_sel:[0,1] op_sel_hi:[1,0]
	v_pk_add_f32 v[66:67], v[66:67], v[66:67] op_sel:[0,1] op_sel_hi:[1,0]
	v_mov_b32_e32 v87, v107
	v_mov_b32_e32 v91, v108
	v_mov_b32_e32 v73, v106
	v_mov_b32_e32 v67, v105
	v_pk_add_f32 v[74:75], v[86:87], v[90:91]
	v_pk_add_f32 v[66:67], v[66:67], v[72:73]
	s_nop 0
	v_pk_add_f32 v[66:67], v[66:67], v[74:75]
	s_nop 0
	v_add_f32_e32 v66, v66, v67
	ds_bpermute_b32 v67, v54, v66
	s_waitcnt lgkmcnt(0)
	v_add_f32_e32 v66, v66, v67
	ds_bpermute_b32 v67, v55, v66
	s_waitcnt lgkmcnt(0)
	v_add_f32_e32 v66, v66, v67
	ds_bpermute_b32 v67, v56, v66
	s_waitcnt lgkmcnt(0)
	v_add_f32_e32 v66, v66, v67
	ds_bpermute_b32 v67, v57, v66
	s_waitcnt lgkmcnt(0)
	v_add_f32_e32 v66, v66, v67
	ds_bpermute_b32 v67, v58, v66
	s_waitcnt lgkmcnt(0)
	v_add_f32_e32 v66, v66, v67
	ds_bpermute_b32 v67, v59, v66
	s_waitcnt lgkmcnt(0)
	v_add_f32_e32 v66, v66, v67
	v_fmamk_f32 v66, v66, 0x3a000000, v60
	v_mul_f32_e32 v67, 0x4f800000, v66
	v_cmp_gt_f32_e32 vcc, s11, v66
	s_nop 1
	v_cndmask_b32_e32 v66, v66, v67, vcc
	v_sqrt_f32_e32 v67, v66
	s_nop 0
	v_add_u32_e32 v68, -1, v67
	v_add_u32_e32 v69, 1, v67
	v_fma_f32 v70, -v68, v67, v66
	v_fma_f32 v71, -v69, v67, v66
	v_cmp_ge_f32_e64 s[4:5], 0, v70
	s_nop 1
	v_cndmask_b32_e64 v67, v67, v68, s[4:5]
	v_cmp_lt_f32_e64 s[4:5], 0, v71
	s_nop 1
	v_cndmask_b32_e64 v67, v67, v69, s[4:5]
	v_mul_f32_e32 v68, 0x37800000, v67
	v_cndmask_b32_e32 v67, v67, v68, vcc
	v_cmp_class_f32_e32 vcc, v66, v61
	s_nop 1
	v_cndmask_b32_e32 v66, v67, v66, vcc
	v_div_scale_f32 v67, s[4:5], v66, v66, 1.0
	v_rcp_f32_e32 v69, v67
	v_div_scale_f32 v68, vcc, 1.0, v66, 1.0
	v_fma_f32 v70, -v67, v69, 1.0
	v_fmac_f32_e32 v69, v70, v69
	v_mul_f32_e32 v70, v68, v69
	v_fma_f32 v71, -v67, v70, v68
	v_fmac_f32_e32 v70, v71, v69
	v_fma_f32 v67, -v67, v70, v68
	v_div_fmas_f32 v67, v67, v69, v70
	v_div_fixup_f32 v66, v67, v66, 1.0
	v_pk_mul_f32 v[68:69], v[66:67], v[94:95] op_sel_hi:[0,1]
	v_pk_mul_f32 v[70:71], v[66:67], v[112:113] op_sel_hi:[0,1]
	v_pk_fma_f32 v[2:3], v[70:71], v[116:117], v[120:121]
	v_pk_fma_f32 v[0:1], v[68:69], v[114:115], v[118:119]
	v_add_co_u32_e32 v48, vcc, s20, v48
	s_nop 0
	v_cvt_pk_bf16_f32 v0, v0, v1
	v_cvt_pk_bf16_f32 v1, v2, v3
	global_store_dwordx2 v[34:35], v[0:1], off
	v_pk_mul_f32 v[68:69], v[66:67], v[82:83] op_sel_hi:[0,1]
	v_pk_mul_f32 v[70:71], v[66:67], v[96:97] op_sel_hi:[0,1]
	v_addc_co_u32_e32 v49, vcc, 0, v49, vcc
	v_pk_mul_f32 v[64:65], v[66:67], v[64:65] op_sel_hi:[0,1]
	v_pk_mul_f32 v[62:63], v[66:67], v[62:63] op_sel_hi:[0,1]
	v_pk_mul_f32 v[50:51], v[66:67], v[50:51] op_sel_hi:[0,1]
	v_pk_mul_f32 v[46:47], v[66:67], v[46:47] op_sel_hi:[0,1]
	v_pk_mul_f32 v[44:45], v[66:67], v[44:45] op_sel_hi:[0,1]
	v_pk_mul_f32 v[42:43], v[66:67], v[42:43] op_sel_hi:[0,1]
	v_pk_mul_f32 v[40:41], v[66:67], v[40:41] op_sel_hi:[0,1]
	v_pk_mul_f32 v[38:39], v[66:67], v[38:39] op_sel_hi:[0,1]
	v_pk_mul_f32 v[36:37], v[66:67], v[36:37] op_sel_hi:[0,1]
	v_pk_fma_f32 v[0:1], v[70:71], v[122:123], v[126:127]
	v_pk_fma_f32 v[2:3], v[68:69], v[124:125], v[128:129]
	v_pk_mul_f32 v[68:69], v[66:67], v[84:85] op_sel_hi:[0,1]
	v_pk_mul_f32 v[70:71], v[66:67], v[98:99] op_sel_hi:[0,1]
	v_cvt_pk_bf16_f32 v0, v0, v1
	v_cvt_pk_bf16_f32 v1, v2, v3
	global_store_dwordx2 v[34:35], v[0:1], off offset:512
	v_pk_fma_f32 v[0:1], v[70:71], v[130:131], v[134:135]
	v_pk_fma_f32 v[2:3], v[68:69], v[132:133], v[136:137]
	s_nop 1
	v_cvt_pk_bf16_f32 v0, v0, v1
	v_cvt_pk_bf16_f32 v1, v2, v3
	global_store_dwordx2 v[34:35], v[0:1], off offset:1024
	v_pk_fma_f32 v[0:1], v[62:63], v[138:139], v[142:143]
	v_pk_fma_f32 v[2:3], v[64:65], v[140:141], v[144:145]
	v_pk_mul_f32 v[48:49], v[66:67], v[52:53] op_sel_hi:[0,1]
	s_nop 0
	v_cvt_pk_bf16_f32 v0, v0, v1
	v_cvt_pk_bf16_f32 v1, v2, v3
	global_store_dwordx2 v[34:35], v[0:1], off offset:1536
	v_pk_fma_f32 v[0:1], v[50:51], v[146:147], v[150:151]
	v_pk_fma_f32 v[2:3], v[48:49], v[148:149], v[152:153]
	s_nop 1
	v_cvt_pk_bf16_f32 v0, v0, v1
	v_cvt_pk_bf16_f32 v1, v2, v3
	global_store_dwordx2 v[34:35], v[0:1], off offset:2048
	v_pk_fma_f32 v[0:1], v[44:45], v[154:155], v[158:159]
	v_pk_fma_f32 v[2:3], v[46:47], v[156:157], v[160:161]
	s_nop 1
	v_cvt_pk_bf16_f32 v0, v0, v1
	v_cvt_pk_bf16_f32 v1, v2, v3
	global_store_dwordx2 v[34:35], v[0:1], off offset:2560
	v_pk_fma_f32 v[0:1], v[40:41], v[162:163], v[166:167]
	v_pk_fma_f32 v[2:3], v[42:43], v[164:165], v[168:169]
	s_nop 1
	v_cvt_pk_bf16_f32 v0, v0, v1
	v_cvt_pk_bf16_f32 v1, v2, v3
	global_store_dwordx2 v[34:35], v[0:1], off offset:3072
	v_pk_fma_f32 v[0:1], v[36:37], v[170:171], v[174:175]
	v_pk_fma_f32 v[2:3], v[38:39], v[172:173], v[176:177]
	s_nop 1
	v_cvt_pk_bf16_f32 v0, v0, v1
	v_cvt_pk_bf16_f32 v1, v2, v3
	global_store_dwordx2 v[34:35], v[0:1], off offset:3584
	s_cbranch_scc0 .LBB0_342

; #define PG8_STAGE(bufoff, gbase, voff) do { _Pragma("unroll") for (int _i = 0; _i < 2; ++_i) \
;         __builtin_amdgcn_global_load_lds((const unsigned*)((const char*)(gbase) + (voff)[_i]), (PG8_LAS unsigned*)(lds + (bufoff) + ldsw + _i * 8192), 16, 0, 0); } while (0)
; #define PG8_LDA(dst, b, h) do { _Pragma("unroll") for (int m = 0; m < 4; ++m) _Pragma("unroll") for (int k = 0; k < 2; ++k) dst[m][k] = *(const PG8_LAS bf16x8*)(lds + PG8_SA(b, h) + aoff + m * 2048 + k * 1024); } while (0)
; #define PG8_LDB(dst, b, h) do { _Pragma("unroll") for (int n = 0; n < 2; ++n) _Pragma("unroll") for (int k = 0; k < 2; ++k) dst[n][k] = *(const PG8_LAS bf16x8*)(lds + PG8_SB(b, h) + boff + n * 2048 + k * 1024); } while (0)
; #define PG8_MMA(ai, bj, At, Bt) do { __builtin_amdgcn_s_setprio(1); _Pragma("unroll") for (int m = 0; m < 4; ++m) _Pragma("unroll") for (int n = 0; n < 2; ++n) _Pragma("unroll") for (int k = 0; k < 2; ++k) \
;         acc[ai][bj][m][n] = __builtin_amdgcn_mfma_f32_16x16x32_bf16(Bt[n][k], At[m][k], acc[ai][bj][m][n], 0, 0, 0); __builtin_amdgcn_s_setprio(0); } while (0)
; #define PG8_WAIT_V(n) asm volatile("s_waitcnt vmcnt(" #n ")" ::: "memory")
; #define PG8_WAIT_L(n) asm volatile("s_waitcnt lgkmcnt(" #n ")" ::: "memory")
; template <class Epi, class Sched, bool ALIGN_EPI = false, bool SP2 = false>
; __device__ __forceinline__ void gemm_phase(PG8_LAS unsigned char* lds, const Gemm g, const Sched& S, const Epi& E) {
;     ...
;             const bool last = (t == nt - 2);
;             const char* a1 = cA + (size_t)(t + 1) * kstep;
;             const char* a2 = last ? nA : cA + (size_t)(t + 2) * kstep; const char* b2 = last ? nB : cB + (size_t)(t + 2) * kstep;
;             const char* a3 = a2 + kstep; const char* b3 = b2 + kstep;
;             if (last && has_next) S.a_ready(nxt);
;             if constexpr (SP2) {
;             PG8_LDB(B0, 0, 0); PG8_LDB(B1, 0, 1); PG8_SCHED; PG8_LDA(At, 0, 0); PG8_STAGE(PG8_SA(1, 1), a1 + hstep, voffA);
;             PG8_WAIT_V(8); PG8_WAIT_L(0); PG8_BAR; PG8_MMA(0, 0, At, B0); PG8_MMA(0, 1, At, B1); PG8_BAR; PG8_SCHED;
;             PG8_LDA(At, 0, 1); PG8_STAGE(PG8_SB(0, 0), b2, voffB); PG8_STAGE(PG8_SB(0, 1), b2 + hstep, voffB); PG8_STAGE(PG8_SA(0, 0), a2, voffA);
;             PG8_WAIT_V(8); PG8_WAIT_L(0); PG8_BAR; PG8_MMA(1, 0, At, B0); PG8_MMA(1, 1, At, B1); PG8_BAR; PG8_SCHED;
.LBB0_552:
	ds_read_b128 v[152:155], v149
	ds_read_b128 v[156:159], v149 offset:1024
	ds_read_b128 v[160:163], v149 offset:2048
	ds_read_b128 v[164:167], v149 offset:3072
	ds_read_b128 v[168:171], v150
	ds_read_b128 v[172:175], v150 offset:1024
	ds_read_b128 v[180:183], v150 offset:2048
	ds_read_b128 v[184:187], v150 offset:3072
	s_add_u32 s34, s26, 0x100
	s_addc_u32 s35, s27, 0
	s_cmpk_eq_i32 s67, 0x54
	s_cselect_b32 s45, s7, s35
	s_cselect_b32 s44, s6, s34
	s_cselect_b32 s37, s9, s66
	s_cselect_b32 s36, s8, s65
	s_add_i32 m0, s29, 0xc000
	ds_read_b128 v[188:191], v151
	ds_read_b128 v[192:195], v151 offset:1024
	ds_read_b128 v[196:199], v151 offset:2048
	ds_read_b128 v[200:203], v151 offset:3072
	ds_read_b128 v[204:207], v151 offset:4096
	ds_read_b128 v[208:211], v151 offset:5120
	ds_read_b128 v[212:215], v151 offset:6144
	ds_read_b128 v[216:219], v151 offset:7168
	global_load_lds_dwordx4 v136, s[26:27]
	s_add_i32 m0, s29, 0xe000
	s_nop 0
	global_load_lds_dwordx4 v138, s[26:27]
	s_waitcnt vmcnt(8)
	s_waitcnt lgkmcnt(0)
	s_barrier
	s_setprio 1
	s_waitcnt lgkmcnt(0)
	v_mfma_f32_16x16x32_bf16 v[124:127], v[152:155], v[188:191], v[124:127]
	v_mfma_f32_16x16x32_bf16 v[120:123], v[160:163], v[188:191], v[120:123]
	v_mfma_f32_16x16x32_bf16 v[116:119], v[152:155], v[196:199], v[116:119]
	v_mfma_f32_16x16x32_bf16 v[108:111], v[160:163], v[196:199], v[108:111]
	v_mfma_f32_16x16x32_bf16 v[100:103], v[152:155], v[204:207], v[100:103]
	v_mfma_f32_16x16x32_bf16 v[92:95], v[160:163], v[204:207], v[92:95]
	v_mfma_f32_16x16x32_bf16 v[84:87], v[152:155], v[212:215], v[84:87]
	v_mfma_f32_16x16x32_bf16 v[76:79], v[160:163], v[212:215], v[76:79]
	v_mfma_f32_16x16x32_bf16 v[124:127], v[156:159], v[192:195], v[124:127]
	v_mfma_f32_16x16x32_bf16 v[120:123], v[164:167], v[192:195], v[120:123]
	v_mfma_f32_16x16x32_bf16 v[116:119], v[156:159], v[200:203], v[116:119]
	v_mfma_f32_16x16x32_bf16 v[108:111], v[164:167], v[200:203], v[108:111]
	v_mfma_f32_16x16x32_bf16 v[100:103], v[156:159], v[208:211], v[100:103]
	v_mfma_f32_16x16x32_bf16 v[92:95], v[164:167], v[208:211], v[92:95]
	v_mfma_f32_16x16x32_bf16 v[84:87], v[156:159], v[216:219], v[84:87]
	v_mfma_f32_16x16x32_bf16 v[76:79], v[164:167], v[216:219], v[76:79]
	s_setprio 0
	s_setprio 1
	v_mfma_f32_16x16x32_bf16 v[112:115], v[168:171], v[188:191], v[112:115]
	v_mfma_f32_16x16x32_bf16 v[104:107], v[180:183], v[188:191], v[104:107]
	v_mfma_f32_16x16x32_bf16 v[96:99], v[168:171], v[196:199], v[96:99]
	v_mfma_f32_16x16x32_bf16 v[88:91], v[180:183], v[196:199], v[88:91]
	v_mfma_f32_16x16x32_bf16 v[80:83], v[168:171], v[204:207], v[80:83]
	v_mfma_f32_16x16x32_bf16 v[72:75], v[180:183], v[204:207], v[72:75]
	v_mfma_f32_16x16x32_bf16 v[68:71], v[168:171], v[212:215], v[68:71]
	v_mfma_f32_16x16x32_bf16 v[64:67], v[180:183], v[212:215], v[64:67]
	v_mfma_f32_16x16x32_bf16 v[112:115], v[172:175], v[192:195], v[112:115]
	v_mfma_f32_16x16x32_bf16 v[104:107], v[184:187], v[192:195], v[104:107]
	v_mfma_f32_16x16x32_bf16 v[96:99], v[172:175], v[200:203], v[96:99]
	v_mfma_f32_16x16x32_bf16 v[88:91], v[184:187], v[200:203], v[88:91]
	v_mfma_f32_16x16x32_bf16 v[80:83], v[172:175], v[208:211], v[80:83]
	v_mfma_f32_16x16x32_bf16 v[72:75], v[184:187], v[208:211], v[72:75]
	v_mfma_f32_16x16x32_bf16 v[68:71], v[172:175], v[216:219], v[68:71]
	v_mfma_f32_16x16x32_bf16 v[64:67], v[184:187], v[216:219], v[64:67]
	s_setprio 0
	s_barrier
	s_add_i32 s26, s55, s1
	s_mov_b32 m0, s26
	ds_read_b128 v[188:191], v151 offset:16384
	ds_read_b128 v[192:195], v151 offset:17408
	ds_read_b128 v[196:199], v151 offset:18432
	ds_read_b128 v[200:203], v151 offset:19456
	ds_read_b128 v[204:207], v151 offset:20480
	ds_read_b128 v[208:211], v151 offset:21504
	ds_read_b128 v[212:215], v151 offset:22528
	ds_read_b128 v[216:219], v151 offset:23552
	global_load_lds_dwordx4 v130, s[36:37]
	s_add_i32 m0, s26, 0x2000
	s_add_u32 s26, s36, 0x160000
	s_addc_u32 s27, s37, 0
	s_add_i32 s30, s56, s1
	global_load_lds_dwordx4 v134, s[36:37]
	s_mov_b32 m0, s30
	s_nop 0
	global_load_lds_dwordx4 v130, s[26:27]
	s_add_i32 m0, s30, 0x2000
	s_nop 0
	global_load_lds_dwordx4 v134, s[26:27]
	s_mov_b32 m0, s29
	s_nop 0
	global_load_lds_dwordx4 v128, s[44:45]
	s_mov_b32 m0, s33
	s_nop 0
	global_load_lds_dwordx4 v132, s[44:45]
	s_waitcnt vmcnt(8)
	s_waitcnt lgkmcnt(0)
	s_barrier
	s_setprio 1
	s_waitcnt lgkmcnt(0)
	v_mfma_f32_16x16x32_bf16 v[60:63], v[152:155], v[188:191], v[60:63]
	v_mfma_f32_16x16x32_bf16 v[56:59], v[160:163], v[188:191], v[56:59]
	v_mfma_f32_16x16x32_bf16 v[52:55], v[152:155], v[196:199], v[52:55]
	v_mfma_f32_16x16x32_bf16 v[44:47], v[160:163], v[196:199], v[44:47]
	v_mfma_f32_16x16x32_bf16 v[36:39], v[152:155], v[204:207], v[36:39]
	v_mfma_f32_16x16x32_bf16 v[28:31], v[160:163], v[204:207], v[28:31]
	v_mfma_f32_16x16x32_bf16 v[20:23], v[152:155], v[212:215], v[20:23]
	v_mfma_f32_16x16x32_bf16 v[12:15], v[160:163], v[212:215], v[12:15]
	v_mfma_f32_16x16x32_bf16 v[60:63], v[156:159], v[192:195], v[60:63]
	v_mfma_f32_16x16x32_bf16 v[56:59], v[164:167], v[192:195], v[56:59]
	v_mfma_f32_16x16x32_bf16 v[52:55], v[156:159], v[200:203], v[52:55]
	v_mfma_f32_16x16x32_bf16 v[44:47], v[164:167], v[200:203], v[44:47]
	v_mfma_f32_16x16x32_bf16 v[36:39], v[156:159], v[208:211], v[36:39]
	v_mfma_f32_16x16x32_bf16 v[28:31], v[164:167], v[208:211], v[28:31]
	v_mfma_f32_16x16x32_bf16 v[20:23], v[156:159], v[216:219], v[20:23]
	v_mfma_f32_16x16x32_bf16 v[12:15], v[164:167], v[216:219], v[12:15]
	s_setprio 0
	s_setprio 1
	v_mfma_f32_16x16x32_bf16 v[48:51], v[168:171], v[188:191], v[48:51]
	v_mfma_f32_16x16x32_bf16 v[40:43], v[180:183], v[188:191], v[40:43]
	v_mfma_f32_16x16x32_bf16 v[32:35], v[168:171], v[196:199], v[32:35]
	v_mfma_f32_16x16x32_bf16 v[24:27], v[180:183], v[196:199], v[24:27]
	v_mfma_f32_16x16x32_bf16 v[16:19], v[168:171], v[204:207], v[16:19]
	v_mfma_f32_16x16x32_bf16 v[8:11], v[180:183], v[204:207], v[8:11]
	v_mfma_f32_16x16x32_bf16 v[4:7], v[168:171], v[212:215], v[4:7]
	v_mfma_f32_16x16x32_bf16 v[0:3], v[180:183], v[212:215], v[0:3]
	v_mfma_f32_16x16x32_bf16 v[48:51], v[172:175], v[192:195], v[48:51]
	v_mfma_f32_16x16x32_bf16 v[40:43], v[184:187], v[192:195], v[40:43]
	v_mfma_f32_16x16x32_bf16 v[32:35], v[172:175], v[200:203], v[32:35]
	v_mfma_f32_16x16x32_bf16 v[24:27], v[184:187], v[200:203], v[24:27]
	v_mfma_f32_16x16x32_bf16 v[16:19], v[172:175], v[208:211], v[16:19]
	v_mfma_f32_16x16x32_bf16 v[8:11], v[184:187], v[208:211], v[8:11]
	v_mfma_f32_16x16x32_bf16 v[4:7], v[172:175], v[216:219], v[4:7]
	v_mfma_f32_16x16x32_bf16 v[0:3], v[184:187], v[216:219], v[0:3]
	s_setprio 0
	s_barrier
; #define PG8_STAGE(bufoff, gbase, voff) do { _Pragma("unroll") for (int _i = 0; _i < 2; ++_i) \
;         __builtin_amdgcn_global_load_lds((const unsigned*)((const char*)(gbase) + (voff)[_i]), (PG8_LAS unsigned*)(lds + (bufoff) + ldsw + _i * 8192), 16, 0, 0); } while (0)
; #define PG8_LDA(dst, b, h) do { _Pragma("unroll") for (int m = 0; m < 4; ++m) _Pragma("unroll") for (int k = 0; k < 2; ++k) dst[m][k] = *(const PG8_LAS bf16x8*)(lds + PG8_SA(b, h) + aoff + m * 2048 + k * 1024); } while (0)
; #define PG8_LDB(dst, b, h) do { _Pragma("unroll") for (int n = 0; n < 2; ++n) _Pragma("unroll") for (int k = 0; k < 2; ++k) dst[n][k] = *(const PG8_LAS bf16x8*)(lds + PG8_SB(b, h) + boff + n * 2048 + k * 1024); } while (0)
; #define PG8_MMA(ai, bj, At, Bt) do { __builtin_amdgcn_s_setprio(1); _Pragma("unroll") for (int m = 0; m < 4; ++m) _Pragma("unroll") for (int n = 0; n < 2; ++n) _Pragma("unroll") for (int k = 0; k < 2; ++k) \
;         acc[ai][bj][m][n] = __builtin_amdgcn_mfma_f32_16x16x32_bf16(Bt[n][k], At[m][k], acc[ai][bj][m][n], 0, 0, 0); __builtin_amdgcn_s_setprio(0); } while (0)
; #define PG8_WAIT_V(n) asm volatile("s_waitcnt vmcnt(" #n ")" ::: "memory")
; #define PG8_WAIT_L(n) asm volatile("s_waitcnt lgkmcnt(" #n ")" ::: "memory")
; #define PG8_BAR __builtin_amdgcn_s_barrier()
; #define PG8_SCHED __builtin_amdgcn_sched_barrier(0)
; template <class Epi, class Sched, bool ALIGN_EPI = false, bool SP2 = false>
; __device__ __forceinline__ void gemm_phase(PG8_LAS unsigned char* lds, const Gemm g, const Sched& S, const Epi& E) {
;     ...
;             PG8_LDB(B0, 1, 0); PG8_LDB(B1, 1, 1); PG8_SCHED; PG8_LDA(At, 1, 0); PG8_STAGE(PG8_SA(0, 1), a2 + hstep, voffA);
;             PG8_WAIT_V(8); PG8_WAIT_L(0); PG8_BAR; PG8_MMA(0, 0, At, B0); PG8_MMA(0, 1, At, B1); PG8_BAR; PG8_SCHED;
;             PG8_LDA(At, 1, 1); PG8_STAGE(PG8_SB(1, 0), b3, voffB); PG8_STAGE(PG8_SB(1, 1), b3 + hstep, voffB); PG8_STAGE(PG8_SA(1, 0), a3, voffA);
;             PG8_WAIT_V(8); PG8_WAIT_L(0); PG8_BAR; PG8_MMA(1, 0, At, B0); PG8_MMA(1, 1, At, B1); PG8_BAR; PG8_SCHED;
	s_add_i32 s30, 0, 0x18000
	s_add_i32 s31, 0, 0x1c000
	v_add_u32_e32 v164, s30, v147
	v_add_u32_e32 v184, s31, v147
	ds_read_b128 v[152:155], v164
	ds_read_b128 v[156:159], v164 offset:1024
	ds_read_b128 v[160:163], v164 offset:2048
	ds_read_b128 v[164:167], v164 offset:3072
	ds_read_b128 v[168:171], v184
	ds_read_b128 v[172:175], v184 offset:1024
	ds_read_b128 v[180:183], v184 offset:2048
	ds_read_b128 v[184:187], v184 offset:3072
	s_add_u32 s26, s44, 0x160000
	s_addc_u32 s27, s45, 0
	s_mov_b32 m0, s46
	ds_read_b128 v[188:191], v151 offset:32768
	ds_read_b128 v[192:195], v151 offset:33792
	ds_read_b128 v[196:199], v151 offset:34816
	ds_read_b128 v[200:203], v151 offset:35840
	ds_read_b128 v[204:207], v151 offset:36864
	ds_read_b128 v[208:211], v151 offset:37888
	ds_read_b128 v[212:215], v151 offset:38912
	ds_read_b128 v[216:219], v151 offset:39936
	global_load_lds_dwordx4 v128, s[26:27]
	s_mov_b32 m0, s47
	s_nop 0
	global_load_lds_dwordx4 v132, s[26:27]
	s_waitcnt vmcnt(8)
	s_waitcnt lgkmcnt(0)
	s_barrier
	s_setprio 1
	s_waitcnt lgkmcnt(0)
	v_mfma_f32_16x16x32_bf16 v[124:127], v[152:155], v[188:191], v[124:127]
	v_mfma_f32_16x16x32_bf16 v[120:123], v[160:163], v[188:191], v[120:123]
	v_mfma_f32_16x16x32_bf16 v[116:119], v[152:155], v[196:199], v[116:119]
	v_mfma_f32_16x16x32_bf16 v[108:111], v[160:163], v[196:199], v[108:111]
	v_mfma_f32_16x16x32_bf16 v[100:103], v[152:155], v[204:207], v[100:103]
	v_mfma_f32_16x16x32_bf16 v[92:95], v[160:163], v[204:207], v[92:95]
	v_mfma_f32_16x16x32_bf16 v[84:87], v[152:155], v[212:215], v[84:87]
	v_mfma_f32_16x16x32_bf16 v[76:79], v[160:163], v[212:215], v[76:79]
	v_mfma_f32_16x16x32_bf16 v[124:127], v[156:159], v[192:195], v[124:127]
	v_mfma_f32_16x16x32_bf16 v[120:123], v[164:167], v[192:195], v[120:123]
	v_mfma_f32_16x16x32_bf16 v[116:119], v[156:159], v[200:203], v[116:119]
	v_mfma_f32_16x16x32_bf16 v[108:111], v[164:167], v[200:203], v[108:111]
	v_mfma_f32_16x16x32_bf16 v[100:103], v[156:159], v[208:211], v[100:103]
	v_mfma_f32_16x16x32_bf16 v[92:95], v[164:167], v[208:211], v[92:95]
	v_mfma_f32_16x16x32_bf16 v[84:87], v[156:159], v[216:219], v[84:87]
	v_mfma_f32_16x16x32_bf16 v[76:79], v[164:167], v[216:219], v[76:79]
	s_setprio 0
	s_setprio 1
	v_mfma_f32_16x16x32_bf16 v[112:115], v[168:171], v[188:191], v[112:115]
	v_mfma_f32_16x16x32_bf16 v[104:107], v[180:183], v[188:191], v[104:107]
	v_mfma_f32_16x16x32_bf16 v[96:99], v[168:171], v[196:199], v[96:99]
	v_mfma_f32_16x16x32_bf16 v[88:91], v[180:183], v[196:199], v[88:91]
	v_mfma_f32_16x16x32_bf16 v[80:83], v[168:171], v[204:207], v[80:83]
	v_mfma_f32_16x16x32_bf16 v[72:75], v[180:183], v[204:207], v[72:75]
	v_mfma_f32_16x16x32_bf16 v[68:71], v[168:171], v[212:215], v[68:71]
	v_mfma_f32_16x16x32_bf16 v[64:67], v[180:183], v[212:215], v[64:67]
	v_mfma_f32_16x16x32_bf16 v[112:115], v[172:175], v[192:195], v[112:115]
	v_mfma_f32_16x16x32_bf16 v[104:107], v[184:187], v[192:195], v[104:107]
	v_mfma_f32_16x16x32_bf16 v[96:99], v[172:175], v[200:203], v[96:99]
	v_mfma_f32_16x16x32_bf16 v[88:91], v[184:187], v[200:203], v[88:91]
	v_mfma_f32_16x16x32_bf16 v[80:83], v[172:175], v[208:211], v[80:83]
	v_mfma_f32_16x16x32_bf16 v[72:75], v[184:187], v[208:211], v[72:75]
	v_mfma_f32_16x16x32_bf16 v[68:71], v[172:175], v[216:219], v[68:71]
	v_mfma_f32_16x16x32_bf16 v[64:67], v[184:187], v[216:219], v[64:67]
	s_setprio 0
	s_barrier
	s_add_i32 s26, s30, s1
	s_mov_b32 m0, s26
	ds_read_b128 v[188:191], v151 offset:49152
	ds_read_b128 v[192:195], v151 offset:50176
	ds_read_b128 v[196:199], v151 offset:51200
	ds_read_b128 v[200:203], v151 offset:52224
	ds_read_b128 v[204:207], v151 offset:53248
	ds_read_b128 v[208:211], v151 offset:54272
	ds_read_b128 v[212:215], v151 offset:55296
	ds_read_b128 v[216:219], v151 offset:56320
	s_add_u32 s10, s36, 0x80
	s_addc_u32 s11, s37, 0
	global_load_lds_dwordx4 v130, s[10:11]
	s_add_i32 m0, s26, 0x2000
	s_add_u32 s26, s36, 0x160080
	s_addc_u32 s27, s37, 0
	s_add_i32 s30, s31, s1
	global_load_lds_dwordx4 v134, s[10:11]
	s_mov_b32 m0, s30
	s_nop 0
	global_load_lds_dwordx4 v130, s[26:27]
	s_add_i32 m0, s30, 0x2000
	s_nop 0
	global_load_lds_dwordx4 v134, s[26:27]
	s_mov_b32 m0, s53
	s_nop 0
	s_add_u32 s10, s44, 0x80
	s_addc_u32 s11, s45, 0
	global_load_lds_dwordx4 v128, s[10:11]
	s_mov_b32 m0, s54
	s_nop 0
	global_load_lds_dwordx4 v132, s[10:11]
	s_waitcnt vmcnt(8)
	s_waitcnt lgkmcnt(0)
	s_barrier
	s_setprio 1
	s_waitcnt lgkmcnt(0)
	v_mfma_f32_16x16x32_bf16 v[60:63], v[152:155], v[188:191], v[60:63]
	v_mfma_f32_16x16x32_bf16 v[56:59], v[160:163], v[188:191], v[56:59]
	v_mfma_f32_16x16x32_bf16 v[52:55], v[152:155], v[196:199], v[52:55]
	v_mfma_f32_16x16x32_bf16 v[44:47], v[160:163], v[196:199], v[44:47]
	v_mfma_f32_16x16x32_bf16 v[36:39], v[152:155], v[204:207], v[36:39]
	v_mfma_f32_16x16x32_bf16 v[28:31], v[160:163], v[204:207], v[28:31]
	v_mfma_f32_16x16x32_bf16 v[20:23], v[152:155], v[212:215], v[20:23]
	v_mfma_f32_16x16x32_bf16 v[12:15], v[160:163], v[212:215], v[12:15]
	v_mfma_f32_16x16x32_bf16 v[60:63], v[156:159], v[192:195], v[60:63]
	v_mfma_f32_16x16x32_bf16 v[56:59], v[164:167], v[192:195], v[56:59]
	v_mfma_f32_16x16x32_bf16 v[52:55], v[156:159], v[200:203], v[52:55]
	v_mfma_f32_16x16x32_bf16 v[44:47], v[164:167], v[200:203], v[44:47]
	v_mfma_f32_16x16x32_bf16 v[36:39], v[156:159], v[208:211], v[36:39]
	v_mfma_f32_16x16x32_bf16 v[28:31], v[164:167], v[208:211], v[28:31]
	v_mfma_f32_16x16x32_bf16 v[20:23], v[156:159], v[216:219], v[20:23]
	v_mfma_f32_16x16x32_bf16 v[12:15], v[164:167], v[216:219], v[12:15]
	s_setprio 0
	s_setprio 1
	v_mfma_f32_16x16x32_bf16 v[48:51], v[168:171], v[188:191], v[48:51]
	v_mfma_f32_16x16x32_bf16 v[40:43], v[180:183], v[188:191], v[40:43]
	v_mfma_f32_16x16x32_bf16 v[32:35], v[168:171], v[196:199], v[32:35]
	v_mfma_f32_16x16x32_bf16 v[24:27], v[180:183], v[196:199], v[24:27]
	v_mfma_f32_16x16x32_bf16 v[16:19], v[168:171], v[204:207], v[16:19]
	v_mfma_f32_16x16x32_bf16 v[8:11], v[180:183], v[204:207], v[8:11]
	v_mfma_f32_16x16x32_bf16 v[4:7], v[168:171], v[212:215], v[4:7]
	v_mfma_f32_16x16x32_bf16 v[0:3], v[180:183], v[212:215], v[0:3]
	v_mfma_f32_16x16x32_bf16 v[48:51], v[172:175], v[192:195], v[48:51]
	v_mfma_f32_16x16x32_bf16 v[40:43], v[184:187], v[192:195], v[40:43]
	v_mfma_f32_16x16x32_bf16 v[32:35], v[172:175], v[200:203], v[32:35]
	v_mfma_f32_16x16x32_bf16 v[24:27], v[184:187], v[200:203], v[24:27]
	v_mfma_f32_16x16x32_bf16 v[16:19], v[172:175], v[208:211], v[16:19]
	v_mfma_f32_16x16x32_bf16 v[8:11], v[184:187], v[208:211], v[8:11]
	v_mfma_f32_16x16x32_bf16 v[4:7], v[172:175], v[216:219], v[4:7]
	v_mfma_f32_16x16x32_bf16 v[0:3], v[184:187], v[216:219], v[0:3]
	s_setprio 0
	s_barrier
; __device__ __forceinline__ unsigned cvt_pk_bf16(float lo, float hi) { unsigned r; asm volatile("v_cvt_pk_bf16_f32 %0, %1, %2" : "=v"(r) : "v"(lo), "v"(hi)); return r; }
; #define PG8_WAIT_V(n) asm volatile("s_waitcnt vmcnt(" #n ")" ::: "memory")
; #define PG8_BAR __builtin_amdgcn_s_barrier()
;     __device__ __forceinline__ void operator()(const f32x4 (&acc)[2][2][4][2], const Unit& u, int wr, int wc, int fr, int fq) const {
;         const int row0 = u.pm * BM + wr * 64 + fr; const int col0 = u.pn * BM + wc * 32 + 8 * fq;
; #pragma unroll
;         for (int ai = 0; ai < 2; ++ai)
; #pragma unroll
;             for (int m = 0; m < 4; ++m) { bf16_t* rowp = O + (size_t)(row0 + ai * HALF + m * 16) * ldc + col0;
; #pragma unroll
;                 for (int bj = 0; bj < 2; ++bj) { const f32x4 v0 = acc[ai][bj][m][0], v1 = acc[ai][bj][m][1];
;                     u32x4 w; w.x = cvt_pk_bf16(v0[0], v0[1]); w.y = cvt_pk_bf16(v0[2], v0[3]); w.z = cvt_pk_bf16(v1[0], v1[1]); w.w = cvt_pk_bf16(v1[2], v1[3]);
;                     *(u32x4*)(rowp + bj * HALF) = w; } }
; template <class Epi, class Sched, bool ALIGN_EPI = false, bool SP2 = false>
; __device__ __forceinline__ void gemm_phase(PG8_LAS unsigned char* lds, const Gemm g, const Sched& S, const Epi& E) {
;     ...
;         if constexpr (!Epi::AFTER_DRAIN) { E(acc, cur, wr, wc, fr, fq); S.done(cur); }
;         if (!has_next) break;
; #pragma unroll
;         for (int a = 0; a < 2; ++a)
; #pragma unroll
;             for (int b = 0; b < 2; ++b)
; #pragma unroll
;                 for (int m = 0; m < 4; ++m)
; #pragma unroll
;                     for (int n = 0; n < 2; ++n) acc[a][b][m][n] = (f32x4){0.f, 0.f, 0.f, 0.f};
;         cur = nxt; cA = nA; cB = nB; ++ui;
;         if constexpr (ALIGN_EPI) { if (wr == 1) PG8_BAR; }
;     }
;     PG8_WAIT_V(0);
;     if constexpr (!ALIGN_EPI) { if (wr == 0) PG8_BAR; }
	s_add_i32 s67, s67, 2
	s_add_u32 s65, s65, 0x100
	s_addc_u32 s66, s66, 0
	s_cmpk_gt_u32 s67, 0x55
	s_mov_b64 s[26:27], s[34:35]
	s_cbranch_scc0 .LBB0_552
	v_lshl_add_u32 v152, s63, 8, v146
	v_lshl_or_b32 v144, s64, 8, v148
	v_ashrrev_i32_e32 v153, 31, v152
	v_ashrrev_i32_e32 v145, 31, v144
	v_lshlrev_b64 v[154:155], 12, v[152:153]
	v_lshl_add_u64 v[154:155], s[90:91], 0, v[154:155]
	v_lshlrev_b64 v[156:157], 1, v[144:145]
	v_lshl_add_u64 v[144:145], v[154:155], 0, v[156:157]
	v_cvt_pk_bf16_f32 v124, v124, v125
	v_cvt_pk_bf16_f32 v125, v126, v127
	v_cvt_pk_bf16_f32 v126, v120, v121
	v_cvt_pk_bf16_f32 v127, v122, v123
	global_store_dwordx4 v[144:145], v[124:127], off
	v_cvt_pk_bf16_f32 v112, v112, v113
	v_cvt_pk_bf16_f32 v113, v114, v115
	v_cvt_pk_bf16_f32 v114, v104, v105
	v_or_b32_e32 v104, 16, v152
	v_ashrrev_i32_e32 v105, 31, v104
	v_lshlrev_b64 v[104:105], 12, v[104:105]
	v_lshl_add_u64 v[104:105], s[90:91], 0, v[104:105]
	v_cvt_pk_bf16_f32 v115, v106, v107
	global_store_dwordx4 v[144:145], v[112:115], off offset:256
	s_mov_b32 s64, s61
	s_mov_b32 s63, s62
	v_lshl_add_u64 v[112:113], v[104:105], 0, v[156:157]
	v_cvt_pk_bf16_f32 v104, v116, v117
	v_cvt_pk_bf16_f32 v105, v118, v119
	v_cvt_pk_bf16_f32 v106, v108, v109
	v_cvt_pk_bf16_f32 v107, v110, v111
	global_store_dwordx4 v[112:113], v[104:107], off
	v_cvt_pk_bf16_f32 v96, v96, v97
	v_cvt_pk_bf16_f32 v97, v98, v99
	v_cvt_pk_bf16_f32 v98, v88, v89
	v_or_b32_e32 v88, 32, v152
	v_ashrrev_i32_e32 v89, 31, v88
	v_lshlrev_b64 v[88:89], 12, v[88:89]
	v_lshl_add_u64 v[88:89], s[90:91], 0, v[88:89]
	v_cvt_pk_bf16_f32 v99, v90, v91
	global_store_dwordx4 v[112:113], v[96:99], off offset:256
	s_mov_b64 s[34:35], s[8:9]
	s_mov_b64 s[26:27], s[6:7]
	v_lshl_add_u64 v[96:97], v[88:89], 0, v[156:157]
	v_cvt_pk_bf16_f32 v88, v100, v101
	v_cvt_pk_bf16_f32 v89, v102, v103
	v_cvt_pk_bf16_f32 v90, v92, v93
	v_cvt_pk_bf16_f32 v91, v94, v95
	global_store_dwordx4 v[96:97], v[88:91], off
	v_cvt_pk_bf16_f32 v80, v80, v81
	v_cvt_pk_bf16_f32 v81, v82, v83
	v_cvt_pk_bf16_f32 v82, v72, v73
	v_or_b32_e32 v72, 48, v152
	v_ashrrev_i32_e32 v73, 31, v72
	v_lshlrev_b64 v[72:73], 12, v[72:73]
	v_lshl_add_u64 v[72:73], s[90:91], 0, v[72:73]
	v_cvt_pk_bf16_f32 v83, v74, v75
	global_store_dwordx4 v[96:97], v[80:83], off offset:256
	s_nop 1
	v_lshl_add_u64 v[80:81], v[72:73], 0, v[156:157]
	v_cvt_pk_bf16_f32 v72, v84, v85
	v_cvt_pk_bf16_f32 v73, v86, v87
	v_cvt_pk_bf16_f32 v74, v76, v77
	v_cvt_pk_bf16_f32 v75, v78, v79
	global_store_dwordx4 v[80:81], v[72:75], off
	v_cvt_pk_bf16_f32 v68, v68, v69
	v_cvt_pk_bf16_f32 v69, v70, v71
	v_cvt_pk_bf16_f32 v70, v64, v65
	v_cvt_pk_bf16_f32 v71, v66, v67
	global_store_dwordx4 v[80:81], v[68:71], off offset:256
	v_cvt_pk_bf16_f32 v60, v60, v61
	v_cvt_pk_bf16_f32 v61, v62, v63
	v_cvt_pk_bf16_f32 v62, v56, v57
	v_add_co_u32_e32 v56, vcc, s57, v144
	v_lshl_add_u64 v[64:65], v[144:145], 0, s[16:17]
	s_nop 0
	v_addc_co_u32_e32 v57, vcc, 0, v145, vcc
	v_cvt_pk_bf16_f32 v63, v58, v59
	global_store_dwordx4 v[56:57], v[60:63], off
	v_cvt_pk_bf16_f32 v48, v48, v49
	v_cvt_pk_bf16_f32 v49, v50, v51
	v_cvt_pk_bf16_f32 v50, v40, v41
	v_cvt_pk_bf16_f32 v51, v42, v43
	global_store_dwordx4 v[64:65], v[48:51], off offset:256
	v_cvt_pk_bf16_f32 v40, v52, v53
	v_cvt_pk_bf16_f32 v41, v54, v55
	v_cvt_pk_bf16_f32 v42, v44, v45
	v_add_co_u32_e32 v44, vcc, s58, v144
	s_nop 0
	v_lshl_add_u64 v[48:49], v[144:145], 0, s[20:21]
	v_addc_co_u32_e32 v45, vcc, 0, v145, vcc
	v_cvt_pk_bf16_f32 v43, v46, v47
	global_store_dwordx4 v[44:45], v[40:43], off
	v_cvt_pk_bf16_f32 v32, v32, v33
	v_cvt_pk_bf16_f32 v33, v34, v35
	v_cvt_pk_bf16_f32 v34, v24, v25
	v_cvt_pk_bf16_f32 v35, v26, v27
	global_store_dwordx4 v[48:49], v[32:35], off offset:256
	v_cvt_pk_bf16_f32 v24, v36, v37
	v_cvt_pk_bf16_f32 v25, v38, v39
	v_cvt_pk_bf16_f32 v26, v28, v29
	v_add_co_u32_e32 v28, vcc, s59, v144
	s_nop 0
	v_lshl_add_u64 v[32:33], v[144:145], 0, s[22:23]
	v_addc_co_u32_e32 v29, vcc, 0, v145, vcc
	v_cvt_pk_bf16_f32 v27, v30, v31
	global_store_dwordx4 v[28:29], v[24:27], off
	v_cvt_pk_bf16_f32 v16, v16, v17
	v_cvt_pk_bf16_f32 v17, v18, v19
	v_cvt_pk_bf16_f32 v18, v8, v9
	v_cvt_pk_bf16_f32 v19, v10, v11
	global_store_dwordx4 v[32:33], v[16:19], off offset:256
	v_cvt_pk_bf16_f32 v8, v20, v21
	v_cvt_pk_bf16_f32 v9, v22, v23
	v_cvt_pk_bf16_f32 v10, v12, v13
	v_add_co_u32_e32 v12, vcc, s60, v144
	s_nop 0
	v_lshl_add_u64 v[16:17], v[144:145], 0, s[24:25]
	v_addc_co_u32_e32 v13, vcc, 0, v145, vcc
	s_and_b64 vcc, exec, s[4:5]
	v_cvt_pk_bf16_f32 v11, v14, v15
	global_store_dwordx4 v[12:13], v[8:11], off
	v_cvt_pk_bf16_f32 v4, v4, v5
	v_cvt_pk_bf16_f32 v5, v6, v7
	v_cvt_pk_bf16_f32 v6, v0, v1
	v_cvt_pk_bf16_f32 v7, v2, v3
	global_store_dwordx4 v[16:17], v[4:7], off offset:256
	s_cbranch_vccz .LBB0_541
	s_waitcnt vmcnt(0)
	s_cmpk_gt_u32 s0, 0xff
	s_cbranch_scc1 .LBB0_556
	s_barrier

; #define PHASE_IDS() int tid_p = threadIdx.x; asm volatile("" : "+v"(tid_p)); const int lane = tid_p & 63; const int wave_p = __builtin_amdgcn_readfirstlane(tid_p >> 6); \
;     const int gw = vcu * NWAVES + wave_p, NGW = G * NWAVES; const size_t gt = (size_t)bx * NTHREADS + tid_p, NGT = (size_t)G * NTHREADS; (void)lane; (void)gw; (void)NGW; (void)gt; (void)NGT
; __global__ void __launch_bounds__(NTHREADS, 2) fwd_megakernel(Args args) {
;     ...
;         float* row = HF + (size_t)m * DM; const float* xr = x + (size_t)m * DM; const bf16* mr = MIXB + (size_t)m * DM; f32x4 v[8]; float s = 0.f;
; #pragma unroll
;         for (int j = 0; j < 8; ++j) { const int c = 4 * (lane + 64 * j); const f32x4 xv = __builtin_nontemporal_load((const f32x4*)(xr + c)); const v2u mv = *(const v2u*)(mr + c);
;     ...
;     { PHASE_IDS();
;     for (int m = gw; m < MTOK; m += NGW) {
;         const float* row = HF + (size_t)m * DM; const bf16* mr = MIXB + (size_t)m * DM; f32x4 v[8]; float s = 0.f;
; #pragma unroll
;         for (int j = 0; j < 8; ++j) { const int c = 4 * (lane + 64 * j); const f32x4 hv = *(const f32x4*)(row + c); const v2u mv = *(const v2u*)(mr + c);
;             v[j] = hv * ALPHA + (f32x4){bflo(mv.x), bfhi(mv.x), bflo(mv.y), bfhi(mv.y)}; s += (v[j][0] + v[j][1]) + (v[j][2] + v[j][3]); }
.LBB0_609:
	s_or_b64 exec, exec, s[2:3]
	s_waitcnt lgkmcnt(0)
	s_barrier
	s_nop 0
	v_readfirstlane_b32 s0, v178
	s_ashr_i32 s0, s0, 6
	s_add_i32 s11, s0, s89
	s_cmpk_gt_i32 s11, 0x7fff
	s_cbranch_scc1 .LBB0_612
	s_mov_b32 s16, s11
	v_readlane_b32 s18, v244, 16
	v_readlane_b32 s19, v244, 17
	v_readlane_b32 s20, v244, 18
	v_readlane_b32 s21, v244, 19
	v_readlane_b32 s22, v244, 20
	v_readlane_b32 s23, v244, 21
	v_mbcnt_lo_u32_b32 v97, -1, 0
	v_mbcnt_hi_u32_b32 v97, -1, v97
	v_lshlrev_b32_e32 v106, 4, v97
	v_add_u32_e32 v107, 0x1000, v106
	v_lshlrev_b32_e32 v108, 3, v97
	v_xor_b32_e32 v109, 1, v97
	v_lshlrev_b32_e32 v109, 2, v109
	v_xor_b32_e32 v110, 2, v97
	v_lshlrev_b32_e32 v110, 2, v110
	v_xor_b32_e32 v111, 4, v97
	v_lshlrev_b32_e32 v111, 2, v111
	v_xor_b32_e32 v240, 8, v97
	v_lshlrev_b32_e32 v240, 2, v240
	v_xor_b32_e32 v241, 16, v97
	v_lshlrev_b32_e32 v241, 2, v241
	v_xor_b32_e32 v242, 32, v97
	v_lshlrev_b32_e32 v242, 2, v242
	v_mov_b32_e32 v105, 0x3727c5ac
	v_mov_b32_e32 v104, 0x260
	s_mov_b32 s10, 0x3f9837f0
	s_mov_b32 s17, 0xf800000
	global_load_dwordx4 v[112:115], v106, s[20:21]
	global_load_dwordx4 v[116:119], v106, s[20:21] offset:1024
	global_load_dwordx4 v[120:123], v106, s[20:21] offset:2048
	global_load_dwordx4 v[124:127], v106, s[20:21] offset:3072
	global_load_dwordx4 v[128:131], v107, s[20:21]
	global_load_dwordx4 v[132:135], v107, s[20:21] offset:1024
	global_load_dwordx4 v[136:139], v107, s[20:21] offset:2048
	global_load_dwordx4 v[140:143], v107, s[20:21] offset:3072
	global_load_dwordx4 v[144:147], v106, s[22:23]
	global_load_dwordx4 v[148:151], v106, s[22:23] offset:1024
	global_load_dwordx4 v[152:155], v106, s[22:23] offset:2048
	global_load_dwordx4 v[156:159], v106, s[22:23] offset:3072
	global_load_dwordx4 v[160:163], v107, s[22:23]
	global_load_dwordx4 v[164:167], v107, s[22:23] offset:1024
	global_load_dwordx4 v[168:171], v107, s[22:23] offset:2048
	global_load_dwordx4 v[172:175], v107, s[22:23] offset:3072
	global_load_dwordx4 v[176:179], v106, s[48:49]
	global_load_dwordx4 v[180:183], v106, s[48:49] offset:1024
	global_load_dwordx4 v[184:187], v106, s[48:49] offset:2048
	global_load_dwordx4 v[188:191], v106, s[48:49] offset:3072
	global_load_dwordx4 v[192:195], v107, s[48:49]
	global_load_dwordx4 v[196:199], v107, s[48:49] offset:1024
	global_load_dwordx4 v[200:203], v107, s[48:49] offset:2048
	global_load_dwordx4 v[204:207], v107, s[48:49] offset:3072
	global_load_dwordx4 v[208:211], v106, s[50:51]
	global_load_dwordx4 v[212:215], v106, s[50:51] offset:1024
	global_load_dwordx4 v[216:219], v106, s[50:51] offset:2048
	global_load_dwordx4 v[220:223], v106, s[50:51] offset:3072
	global_load_dwordx4 v[224:227], v107, s[50:51]
	global_load_dwordx4 v[228:231], v107, s[50:51] offset:1024
	global_load_dwordx4 v[232:235], v107, s[50:51] offset:2048
	global_load_dwordx4 v[236:239], v107, s[50:51] offset:3072
	s_lshl_b32 s0, s16, 13
	s_add_u32 s2, s38, s0
	s_addc_u32 s3, s39, 0
	s_add_u32 s4, s18, s0
	s_addc_u32 s5, s19, 0
	s_lshl_b32 s0, s16, 12
	s_add_u32 s6, s40, s0
	s_addc_u32 s7, s41, 0
	s_add_u32 s8, s6, 0x7c00000
	s_addc_u32 s9, s7, 0
	s_add_u32 s6, s6, 0xfc00000
	s_addc_u32 s7, s7, 0
	s_lshl_b32 s12, s28, 13
	s_mov_b32 s13, 0
	s_lshl_b32 s14, s28, 12
	s_mov_b32 s15, 0
.Lp9r_loop:
	global_load_dwordx4 v[0:3], v106, s[4:5] nt
	global_load_dwordx4 v[4:7], v106, s[4:5] offset:1024 nt
	global_load_dwordx4 v[8:11], v106, s[4:5] offset:2048 nt
	global_load_dwordx4 v[12:15], v106, s[4:5] offset:3072 nt
	global_load_dwordx4 v[16:19], v107, s[4:5] nt
	global_load_dwordx4 v[20:23], v107, s[4:5] offset:1024 nt
	global_load_dwordx4 v[24:27], v107, s[4:5] offset:2048 nt
	global_load_dwordx4 v[28:31], v107, s[4:5] offset:3072 nt
	global_load_dwordx2 v[32:33], v108, s[6:7]
	global_load_dwordx2 v[34:35], v108, s[6:7] offset:512
	global_load_dwordx2 v[36:37], v108, s[6:7] offset:1024
	global_load_dwordx2 v[38:39], v108, s[6:7] offset:1536
	global_load_dwordx2 v[40:41], v108, s[6:7] offset:2048
	global_load_dwordx2 v[42:43], v108, s[6:7] offset:2560
	global_load_dwordx2 v[44:45], v108, s[6:7] offset:3072
	global_load_dwordx2 v[46:47], v108, s[6:7] offset:3584
	global_load_dwordx2 v[48:49], v108, s[8:9]
	global_load_dwordx2 v[50:51], v108, s[8:9] offset:512
	global_load_dwordx2 v[52:53], v108, s[8:9] offset:1024
	global_load_dwordx2 v[54:55], v108, s[8:9] offset:1536
	global_load_dwordx2 v[56:57], v108, s[8:9] offset:2048
	global_load_dwordx2 v[58:59], v108, s[8:9] offset:2560
	global_load_dwordx2 v[60:61], v108, s[8:9] offset:3072
	global_load_dwordx2 v[62:63], v108, s[8:9] offset:3584
	s_add_u32 s4, s4, s12
	s_addc_u32 s5, s5, s13
	s_add_u32 s6, s6, s14
	s_addc_u32 s7, s7, s15
	s_add_u32 s8, s8, s14
	s_addc_u32 s9, s9, s15
	s_waitcnt vmcnt(8)
; __global__ void __launch_bounds__(NTHREADS, 2) fwd_megakernel(Args args) {
;     ...
;         float* row = HF + (size_t)m * DM; const float* xr = x + (size_t)m * DM; const bf16* mr = MIXB + (size_t)m * DM; f32x4 v[8]; float s = 0.f;
; #pragma unroll
;         for (int j = 0; j < 8; ++j) { const int c = 4 * (lane + 64 * j); const f32x4 xv = __builtin_nontemporal_load((const f32x4*)(xr + c)); const v2u mv = *(const v2u*)(mr + c);
;             v[j] = xv * ALPHA + (f32x4){bflo(mv.x), bfhi(mv.x), bflo(mv.y), bfhi(mv.y)}; s += (v[j][0] + v[j][1]) + (v[j][2] + v[j][3]); }
;         const float mean = wave_sum(s) * (1.f / DM); float s2 = 0.f;
; #pragma unroll
;         for (int j = 0; j < 8; ++j) { v[j] = v[j] - mean; s2 += (v[j][0] * v[j][0] + v[j][1] * v[j][1]) + (v[j][2] * v[j][2] + v[j][3] * v[j][3]); }
	v_lshlrev_b32_e32 v64, 16, v32
	v_and_b32_e32 v65, 0xffff0000, v32
	v_lshlrev_b32_e32 v66, 16, v33
	v_and_b32_e32 v67, 0xffff0000, v33
	v_lshlrev_b32_e32 v68, 16, v34
	v_and_b32_e32 v69, 0xffff0000, v34
	v_lshlrev_b32_e32 v70, 16, v35
	v_and_b32_e32 v71, 0xffff0000, v35
	v_lshlrev_b32_e32 v72, 16, v36
	v_and_b32_e32 v73, 0xffff0000, v36
	v_lshlrev_b32_e32 v74, 16, v37
	v_and_b32_e32 v75, 0xffff0000, v37
	v_lshlrev_b32_e32 v76, 16, v38
	v_and_b32_e32 v77, 0xffff0000, v38
	v_lshlrev_b32_e32 v78, 16, v39
	v_and_b32_e32 v79, 0xffff0000, v39
	v_lshlrev_b32_e32 v80, 16, v40
	v_and_b32_e32 v81, 0xffff0000, v40
	v_lshlrev_b32_e32 v82, 16, v41
	v_and_b32_e32 v83, 0xffff0000, v41
	v_lshlrev_b32_e32 v84, 16, v42
	v_and_b32_e32 v85, 0xffff0000, v42
	v_lshlrev_b32_e32 v86, 16, v43
	v_and_b32_e32 v87, 0xffff0000, v43
	v_lshlrev_b32_e32 v88, 16, v44
	v_and_b32_e32 v89, 0xffff0000, v44
	v_lshlrev_b32_e32 v90, 16, v45
	v_and_b32_e32 v91, 0xffff0000, v45
	v_lshlrev_b32_e32 v92, 16, v46
	v_and_b32_e32 v93, 0xffff0000, v46
	v_lshlrev_b32_e32 v94, 16, v47
	v_and_b32_e32 v95, 0xffff0000, v47
	v_pk_fma_f32 v[0:1], v[0:1], s[10:11], v[64:65] op_sel_hi:[1,0,1]
	v_pk_fma_f32 v[2:3], v[2:3], s[10:11], v[66:67] op_sel_hi:[1,0,1]
	v_pk_fma_f32 v[4:5], v[4:5], s[10:11], v[68:69] op_sel_hi:[1,0,1]
	v_pk_fma_f32 v[6:7], v[6:7], s[10:11], v[70:71] op_sel_hi:[1,0,1]
	v_pk_fma_f32 v[8:9], v[8:9], s[10:11], v[72:73] op_sel_hi:[1,0,1]
	v_pk_fma_f32 v[10:11], v[10:11], s[10:11], v[74:75] op_sel_hi:[1,0,1]
	v_pk_fma_f32 v[12:13], v[12:13], s[10:11], v[76:77] op_sel_hi:[1,0,1]
	v_pk_fma_f32 v[14:15], v[14:15], s[10:11], v[78:79] op_sel_hi:[1,0,1]
	v_pk_fma_f32 v[16:17], v[16:17], s[10:11], v[80:81] op_sel_hi:[1,0,1]
	v_pk_fma_f32 v[18:19], v[18:19], s[10:11], v[82:83] op_sel_hi:[1,0,1]
	v_pk_fma_f32 v[20:21], v[20:21], s[10:11], v[84:85] op_sel_hi:[1,0,1]
	v_pk_fma_f32 v[22:23], v[22:23], s[10:11], v[86:87] op_sel_hi:[1,0,1]
	v_pk_fma_f32 v[24:25], v[24:25], s[10:11], v[88:89] op_sel_hi:[1,0,1]
	v_pk_fma_f32 v[26:27], v[26:27], s[10:11], v[90:91] op_sel_hi:[1,0,1]
	v_pk_fma_f32 v[28:29], v[28:29], s[10:11], v[92:93] op_sel_hi:[1,0,1]
	v_pk_fma_f32 v[30:31], v[30:31], s[10:11], v[94:95] op_sel_hi:[1,0,1]
	v_pk_add_f32 v[64:65], v[0:1], v[2:3]
	v_pk_add_f32 v[66:67], v[4:5], v[6:7]
	v_pk_add_f32 v[68:69], v[8:9], v[10:11]
	v_pk_add_f32 v[70:71], v[12:13], v[14:15]
	v_pk_add_f32 v[72:73], v[16:17], v[18:19]
	v_pk_add_f32 v[74:75], v[20:21], v[22:23]
	v_pk_add_f32 v[76:77], v[24:25], v[26:27]
	v_pk_add_f32 v[78:79], v[28:29], v[30:31]
	v_pk_add_f32 v[80:81], v[64:65], v[66:67]
	v_pk_add_f32 v[82:83], v[68:69], v[70:71]
	v_pk_add_f32 v[84:85], v[72:73], v[74:75]
	v_pk_add_f32 v[86:87], v[76:77], v[78:79]
	v_pk_add_f32 v[64:65], v[80:81], v[82:83]
	v_pk_add_f32 v[66:67], v[84:85], v[86:87]
	s_nop 0
	v_pk_add_f32 v[64:65], v[64:65], v[66:67]
	s_nop 0
	v_add_f32_e32 v96, v64, v65
	ds_bpermute_b32 v97, v109, v96
	s_waitcnt lgkmcnt(0)
	v_add_f32_e32 v96, v96, v97
	ds_bpermute_b32 v97, v110, v96
	s_waitcnt lgkmcnt(0)
	v_add_f32_e32 v96, v96, v97
	ds_bpermute_b32 v97, v111, v96
	s_waitcnt lgkmcnt(0)
	v_add_f32_e32 v96, v96, v97
	ds_bpermute_b32 v97, v240, v96
	s_waitcnt lgkmcnt(0)
	v_add_f32_e32 v96, v96, v97
	ds_bpermute_b32 v97, v241, v96
	s_waitcnt lgkmcnt(0)
	v_add_f32_e32 v96, v96, v97
	ds_bpermute_b32 v97, v242, v96
	s_waitcnt lgkmcnt(0)
	v_add_f32_e32 v96, v96, v97
	v_mul_f32_e32 v96, 0xba000000, v96
	v_pk_add_f32 v[0:1], v[0:1], v[96:97] op_sel_hi:[1,0]
	v_pk_add_f32 v[2:3], v[2:3], v[96:97] op_sel_hi:[1,0]
	v_pk_add_f32 v[4:5], v[4:5], v[96:97] op_sel_hi:[1,0]
	v_pk_add_f32 v[6:7], v[6:7], v[96:97] op_sel_hi:[1,0]
	v_pk_add_f32 v[8:9], v[8:9], v[96:97] op_sel_hi:[1,0]
	v_pk_add_f32 v[10:11], v[10:11], v[96:97] op_sel_hi:[1,0]
	v_pk_add_f32 v[12:13], v[12:13], v[96:97] op_sel_hi:[1,0]
	v_pk_add_f32 v[14:15], v[14:15], v[96:97] op_sel_hi:[1,0]
	v_pk_add_f32 v[16:17], v[16:17], v[96:97] op_sel_hi:[1,0]
	v_pk_add_f32 v[18:19], v[18:19], v[96:97] op_sel_hi:[1,0]
	v_pk_add_f32 v[20:21], v[20:21], v[96:97] op_sel_hi:[1,0]
	v_pk_add_f32 v[22:23], v[22:23], v[96:97] op_sel_hi:[1,0]
	v_pk_add_f32 v[24:25], v[24:25], v[96:97] op_sel_hi:[1,0]
	v_pk_add_f32 v[26:27], v[26:27], v[96:97] op_sel_hi:[1,0]
	v_pk_add_f32 v[28:29], v[28:29], v[96:97] op_sel_hi:[1,0]
	v_pk_add_f32 v[30:31], v[30:31], v[96:97] op_sel_hi:[1,0]
	v_pk_mul_f32 v[64:65], v[0:1], v[0:1]
	v_pk_mul_f32 v[66:67], v[4:5], v[4:5]
	v_pk_mul_f32 v[68:69], v[8:9], v[8:9]
	v_pk_mul_f32 v[70:71], v[12:13], v[12:13]
	v_pk_fma_f32 v[64:65], v[2:3], v[2:3], v[64:65]
	v_pk_fma_f32 v[66:67], v[6:7], v[6:7], v[66:67]
	v_pk_fma_f32 v[68:69], v[10:11], v[10:11], v[68:69]
	v_pk_fma_f32 v[70:71], v[14:15], v[14:15], v[70:71]
	v_pk_fma_f32 v[64:65], v[16:17], v[16:17], v[64:65]
	v_pk_fma_f32 v[66:67], v[20:21], v[20:21], v[66:67]
	v_pk_fma_f32 v[68:69], v[24:25], v[24:25], v[68:69]
	v_pk_fma_f32 v[70:71], v[28:29], v[28:29], v[70:71]
	v_pk_fma_f32 v[64:65], v[18:19], v[18:19], v[64:65]
	v_pk_fma_f32 v[66:67], v[22:23], v[22:23], v[66:67]
	v_pk_fma_f32 v[68:69], v[26:27], v[26:27], v[68:69]
	v_pk_fma_f32 v[70:71], v[30:31], v[30:31], v[70:71]
	v_pk_add_f32 v[64:65], v[64:65], v[66:67]
	v_pk_add_f32 v[68:69], v[68:69], v[70:71]
	s_nop 0
	v_pk_add_f32 v[64:65], v[64:65], v[68:69]
	s_nop 0
	v_add_f32_e32 v96, v64, v65
	ds_bpermute_b32 v97, v109, v96
	s_waitcnt lgkmcnt(0)
	v_add_f32_e32 v96, v96, v97
	ds_bpermute_b32 v97, v110, v96
	s_waitcnt lgkmcnt(0)
	v_add_f32_e32 v96, v96, v97
	ds_bpermute_b32 v97, v111, v96
	s_waitcnt lgkmcnt(0)
	v_add_f32_e32 v96, v96, v97
	ds_bpermute_b32 v97, v240, v96
	s_waitcnt lgkmcnt(0)
; __device__ __forceinline__ unsigned cvtpk(float lo, float hi) { f32x2_t v = {lo, hi}; bf16x2_t b = __builtin_convertvector(v, bf16x2_t); return __builtin_bit_cast(unsigned, b); }
; __global__ void __launch_bounds__(NTHREADS, 2) fwd_megakernel(Args args) {
;     ...
;         const float rstd = 1.f / sqrtf(wave_sum(s2) * (1.f / DM) + LN_EPS);
; #pragma unroll
;         for (int j = 0; j < 8; ++j) { const int c = 4 * (lane + 64 * j); const f32x4 gg = *(const f32x4*)(ln1_g + c), bb = *(const f32x4*)(ln1_b + c);
;             const f32x4 o = v[j] * rstd * gg + bb; *(f32x4*)(row + c) = o;
;             v2u wv; wv.x = cvtpk(o[0], o[1]); wv.y = cvtpk(o[2], o[3]); *(v2u*)(HB + (size_t)m * DM + c) = wv; }
;     ...
;         for (int j = 0; j < 8; ++j) { const int c = 4 * (lane + 64 * j); const f32x4 hv = *(const f32x4*)(row + c); const v2u mv = *(const v2u*)(mr + c);
;             v[j] = hv * ALPHA + (f32x4){bflo(mv.x), bfhi(mv.x), bflo(mv.y), bfhi(mv.y)}; s += (v[j][0] + v[j][1]) + (v[j][2] + v[j][3]); }
;         const float mean = wave_sum(s) * (1.f / DM); float s2 = 0.f;
	v_add_f32_e32 v96, v96, v97
	ds_bpermute_b32 v97, v241, v96
	s_waitcnt lgkmcnt(0)
	v_add_f32_e32 v96, v96, v97
	ds_bpermute_b32 v97, v242, v96
	s_waitcnt lgkmcnt(0)
	v_add_f32_e32 v96, v96, v97
	v_fmamk_f32 v98, v96, 0x3a000000, v105
	v_mul_f32_e32 v99, 0x4f800000, v98
	v_cmp_gt_f32_e32 vcc, s17, v98
	s_nop 1
	v_cndmask_b32_e32 v98, v98, v99, vcc
	v_sqrt_f32_e32 v99, v98
	s_nop 0
	v_add_u32_e32 v100, -1, v99
	v_add_u32_e32 v101, 1, v99
	v_fma_f32 v102, -v100, v99, v98
	v_fma_f32 v103, -v101, v99, v98
	v_cmp_ge_f32_e64 s[0:1], 0, v102
	s_nop 1
	v_cndmask_b32_e64 v99, v99, v100, s[0:1]
	v_cmp_lt_f32_e64 s[0:1], 0, v103
	s_nop 1
	v_cndmask_b32_e64 v99, v99, v101, s[0:1]
	v_mul_f32_e32 v100, 0x37800000, v99
	v_cndmask_b32_e32 v99, v99, v100, vcc
	v_cmp_class_f32_e32 vcc, v98, v104
	s_nop 1
	v_cndmask_b32_e32 v98, v99, v98, vcc
	v_div_scale_f32 v99, s[0:1], v98, v98, 1.0
	v_rcp_f32_e32 v101, v99
	v_div_scale_f32 v100, vcc, 1.0, v98, 1.0
	v_fma_f32 v102, -v99, v101, 1.0
	v_fmac_f32_e32 v101, v102, v101
	v_mul_f32_e32 v102, v100, v101
	v_fma_f32 v103, -v99, v102, v100
	v_fmac_f32_e32 v102, v103, v101
	v_fma_f32 v99, -v99, v102, v100
	v_div_fmas_f32 v99, v99, v101, v102
	v_div_fixup_f32 v98, v99, v98, 1.0
	v_pk_mul_f32 v[0:1], v[98:99], v[0:1] op_sel_hi:[0,1]
	v_pk_mul_f32 v[2:3], v[98:99], v[2:3] op_sel_hi:[0,1]
	v_pk_mul_f32 v[4:5], v[98:99], v[4:5] op_sel_hi:[0,1]
	v_pk_mul_f32 v[6:7], v[98:99], v[6:7] op_sel_hi:[0,1]
	v_pk_mul_f32 v[8:9], v[98:99], v[8:9] op_sel_hi:[0,1]
	v_pk_mul_f32 v[10:11], v[98:99], v[10:11] op_sel_hi:[0,1]
	v_pk_mul_f32 v[12:13], v[98:99], v[12:13] op_sel_hi:[0,1]
	v_pk_mul_f32 v[14:15], v[98:99], v[14:15] op_sel_hi:[0,1]
	v_pk_mul_f32 v[16:17], v[98:99], v[16:17] op_sel_hi:[0,1]
	v_pk_mul_f32 v[18:19], v[98:99], v[18:19] op_sel_hi:[0,1]
	v_pk_mul_f32 v[20:21], v[98:99], v[20:21] op_sel_hi:[0,1]
	v_pk_mul_f32 v[22:23], v[98:99], v[22:23] op_sel_hi:[0,1]
	v_pk_mul_f32 v[24:25], v[98:99], v[24:25] op_sel_hi:[0,1]
	v_pk_mul_f32 v[26:27], v[98:99], v[26:27] op_sel_hi:[0,1]
	v_pk_mul_f32 v[28:29], v[98:99], v[28:29] op_sel_hi:[0,1]
	v_pk_mul_f32 v[30:31], v[98:99], v[30:31] op_sel_hi:[0,1]
	v_pk_fma_f32 v[0:1], v[0:1], v[112:113], v[144:145]
	v_pk_fma_f32 v[2:3], v[2:3], v[114:115], v[146:147]
	v_pk_fma_f32 v[4:5], v[4:5], v[116:117], v[148:149]
	v_pk_fma_f32 v[6:7], v[6:7], v[118:119], v[150:151]
	v_pk_fma_f32 v[8:9], v[8:9], v[120:121], v[152:153]
	v_pk_fma_f32 v[10:11], v[10:11], v[122:123], v[154:155]
	v_pk_fma_f32 v[12:13], v[12:13], v[124:125], v[156:157]
	v_pk_fma_f32 v[14:15], v[14:15], v[126:127], v[158:159]
	v_pk_fma_f32 v[16:17], v[16:17], v[128:129], v[160:161]
	v_pk_fma_f32 v[18:19], v[18:19], v[130:131], v[162:163]
	v_pk_fma_f32 v[20:21], v[20:21], v[132:133], v[164:165]
	v_pk_fma_f32 v[22:23], v[22:23], v[134:135], v[166:167]
	v_pk_fma_f32 v[24:25], v[24:25], v[136:137], v[168:169]
	v_pk_fma_f32 v[26:27], v[26:27], v[138:139], v[170:171]
	v_pk_fma_f32 v[28:29], v[28:29], v[140:141], v[172:173]
	v_pk_fma_f32 v[30:31], v[30:31], v[142:143], v[174:175]
	s_waitcnt vmcnt(0)
	v_lshlrev_b32_e32 v64, 16, v48
	v_and_b32_e32 v65, 0xffff0000, v48
	v_lshlrev_b32_e32 v66, 16, v49
	v_and_b32_e32 v67, 0xffff0000, v49
	v_lshlrev_b32_e32 v68, 16, v50
	v_and_b32_e32 v69, 0xffff0000, v50
	v_lshlrev_b32_e32 v70, 16, v51
	v_and_b32_e32 v71, 0xffff0000, v51
	v_lshlrev_b32_e32 v72, 16, v52
	v_and_b32_e32 v73, 0xffff0000, v52
	v_lshlrev_b32_e32 v74, 16, v53
	v_and_b32_e32 v75, 0xffff0000, v53
	v_lshlrev_b32_e32 v76, 16, v54
	v_and_b32_e32 v77, 0xffff0000, v54
	v_lshlrev_b32_e32 v78, 16, v55
	v_and_b32_e32 v79, 0xffff0000, v55
	v_lshlrev_b32_e32 v80, 16, v56
	v_and_b32_e32 v81, 0xffff0000, v56
	v_lshlrev_b32_e32 v82, 16, v57
	v_and_b32_e32 v83, 0xffff0000, v57
	v_lshlrev_b32_e32 v84, 16, v58
	v_and_b32_e32 v85, 0xffff0000, v58
	v_lshlrev_b32_e32 v86, 16, v59
	v_and_b32_e32 v87, 0xffff0000, v59
	v_lshlrev_b32_e32 v88, 16, v60
	v_and_b32_e32 v89, 0xffff0000, v60
	v_lshlrev_b32_e32 v90, 16, v61
	v_and_b32_e32 v91, 0xffff0000, v61
	v_lshlrev_b32_e32 v92, 16, v62
	v_and_b32_e32 v93, 0xffff0000, v62
	v_lshlrev_b32_e32 v94, 16, v63
	v_and_b32_e32 v95, 0xffff0000, v63
	v_pk_fma_f32 v[0:1], v[0:1], s[10:11], v[64:65] op_sel_hi:[1,0,1]
	v_pk_fma_f32 v[2:3], v[2:3], s[10:11], v[66:67] op_sel_hi:[1,0,1]
	v_pk_fma_f32 v[4:5], v[4:5], s[10:11], v[68:69] op_sel_hi:[1,0,1]
	v_pk_fma_f32 v[6:7], v[6:7], s[10:11], v[70:71] op_sel_hi:[1,0,1]
	v_pk_fma_f32 v[8:9], v[8:9], s[10:11], v[72:73] op_sel_hi:[1,0,1]
	v_pk_fma_f32 v[10:11], v[10:11], s[10:11], v[74:75] op_sel_hi:[1,0,1]
	v_pk_fma_f32 v[12:13], v[12:13], s[10:11], v[76:77] op_sel_hi:[1,0,1]
	v_pk_fma_f32 v[14:15], v[14:15], s[10:11], v[78:79] op_sel_hi:[1,0,1]
	v_pk_fma_f32 v[16:17], v[16:17], s[10:11], v[80:81] op_sel_hi:[1,0,1]
	v_pk_fma_f32 v[18:19], v[18:19], s[10:11], v[82:83] op_sel_hi:[1,0,1]
	v_pk_fma_f32 v[20:21], v[20:21], s[10:11], v[84:85] op_sel_hi:[1,0,1]
	v_pk_fma_f32 v[22:23], v[22:23], s[10:11], v[86:87] op_sel_hi:[1,0,1]
	v_pk_fma_f32 v[24:25], v[24:25], s[10:11], v[88:89] op_sel_hi:[1,0,1]
	v_pk_fma_f32 v[26:27], v[26:27], s[10:11], v[90:91] op_sel_hi:[1,0,1]
	v_pk_fma_f32 v[28:29], v[28:29], s[10:11], v[92:93] op_sel_hi:[1,0,1]
	v_pk_fma_f32 v[30:31], v[30:31], s[10:11], v[94:95] op_sel_hi:[1,0,1]
	v_pk_add_f32 v[64:65], v[0:1], v[2:3]
	v_pk_add_f32 v[66:67], v[4:5], v[6:7]
	v_pk_add_f32 v[68:69], v[8:9], v[10:11]
	v_pk_add_f32 v[70:71], v[12:13], v[14:15]
	v_pk_add_f32 v[72:73], v[16:17], v[18:19]
	v_pk_add_f32 v[74:75], v[20:21], v[22:23]
	v_pk_add_f32 v[76:77], v[24:25], v[26:27]
	v_pk_add_f32 v[78:79], v[28:29], v[30:31]
	v_pk_add_f32 v[80:81], v[64:65], v[66:67]
	v_pk_add_f32 v[82:83], v[68:69], v[70:71]
	v_pk_add_f32 v[84:85], v[72:73], v[74:75]
	v_pk_add_f32 v[86:87], v[76:77], v[78:79]
	v_pk_add_f32 v[64:65], v[80:81], v[82:83]
	v_pk_add_f32 v[66:67], v[84:85], v[86:87]
	s_nop 0
	v_pk_add_f32 v[64:65], v[64:65], v[66:67]
	s_nop 0
	v_add_f32_e32 v96, v64, v65
	ds_bpermute_b32 v97, v109, v96
	s_waitcnt lgkmcnt(0)
; __global__ void __launch_bounds__(NTHREADS, 2) fwd_megakernel(Args args) {
;     ...
;         const float mean = wave_sum(s) * (1.f / DM); float s2 = 0.f;
; #pragma unroll
;         for (int j = 0; j < 8; ++j) { v[j] = v[j] - mean; s2 += (v[j][0] * v[j][0] + v[j][1] * v[j][1]) + (v[j][2] * v[j][2] + v[j][3] * v[j][3]); }
;         const float rstd = 1.f / sqrtf(wave_sum(s2) * (1.f / DM) + LN_EPS);
; #pragma unroll
;         for (int j = 0; j < 8; ++j) { const int c = 4 * (lane + 64 * j); const f32x4 gg = *(const f32x4*)(ln2_g + c), bb = *(const f32x4*)(ln2_b + c);
;             __builtin_nontemporal_store(v[j] * rstd * gg + bb, (f32x4*)(args.out + (size_t)m * DM + c)); }
	v_add_f32_e32 v96, v96, v97
	ds_bpermute_b32 v97, v110, v96
	s_waitcnt lgkmcnt(0)
	v_add_f32_e32 v96, v96, v97
	ds_bpermute_b32 v97, v111, v96
	s_waitcnt lgkmcnt(0)
	v_add_f32_e32 v96, v96, v97
	ds_bpermute_b32 v97, v240, v96
	s_waitcnt lgkmcnt(0)
	v_add_f32_e32 v96, v96, v97
	ds_bpermute_b32 v97, v241, v96
	s_waitcnt lgkmcnt(0)
	v_add_f32_e32 v96, v96, v97
	ds_bpermute_b32 v97, v242, v96
	s_waitcnt lgkmcnt(0)
	v_add_f32_e32 v96, v96, v97
	v_mul_f32_e32 v96, 0xba000000, v96
	v_pk_add_f32 v[0:1], v[0:1], v[96:97] op_sel_hi:[1,0]
	v_pk_add_f32 v[2:3], v[2:3], v[96:97] op_sel_hi:[1,0]
	v_pk_add_f32 v[4:5], v[4:5], v[96:97] op_sel_hi:[1,0]
	v_pk_add_f32 v[6:7], v[6:7], v[96:97] op_sel_hi:[1,0]
	v_pk_add_f32 v[8:9], v[8:9], v[96:97] op_sel_hi:[1,0]
	v_pk_add_f32 v[10:11], v[10:11], v[96:97] op_sel_hi:[1,0]
	v_pk_add_f32 v[12:13], v[12:13], v[96:97] op_sel_hi:[1,0]
	v_pk_add_f32 v[14:15], v[14:15], v[96:97] op_sel_hi:[1,0]
	v_pk_add_f32 v[16:17], v[16:17], v[96:97] op_sel_hi:[1,0]
	v_pk_add_f32 v[18:19], v[18:19], v[96:97] op_sel_hi:[1,0]
	v_pk_add_f32 v[20:21], v[20:21], v[96:97] op_sel_hi:[1,0]
	v_pk_add_f32 v[22:23], v[22:23], v[96:97] op_sel_hi:[1,0]
	v_pk_add_f32 v[24:25], v[24:25], v[96:97] op_sel_hi:[1,0]
	v_pk_add_f32 v[26:27], v[26:27], v[96:97] op_sel_hi:[1,0]
	v_pk_add_f32 v[28:29], v[28:29], v[96:97] op_sel_hi:[1,0]
	v_pk_add_f32 v[30:31], v[30:31], v[96:97] op_sel_hi:[1,0]
	v_pk_mul_f32 v[64:65], v[0:1], v[0:1]
	v_pk_mul_f32 v[66:67], v[4:5], v[4:5]
	v_pk_mul_f32 v[68:69], v[8:9], v[8:9]
	v_pk_mul_f32 v[70:71], v[12:13], v[12:13]
	v_pk_fma_f32 v[64:65], v[2:3], v[2:3], v[64:65]
	v_pk_fma_f32 v[66:67], v[6:7], v[6:7], v[66:67]
	v_pk_fma_f32 v[68:69], v[10:11], v[10:11], v[68:69]
	v_pk_fma_f32 v[70:71], v[14:15], v[14:15], v[70:71]
	v_pk_fma_f32 v[64:65], v[16:17], v[16:17], v[64:65]
	v_pk_fma_f32 v[66:67], v[20:21], v[20:21], v[66:67]
	v_pk_fma_f32 v[68:69], v[24:25], v[24:25], v[68:69]
	v_pk_fma_f32 v[70:71], v[28:29], v[28:29], v[70:71]
	v_pk_fma_f32 v[64:65], v[18:19], v[18:19], v[64:65]
	v_pk_fma_f32 v[66:67], v[22:23], v[22:23], v[66:67]
	v_pk_fma_f32 v[68:69], v[26:27], v[26:27], v[68:69]
	v_pk_fma_f32 v[70:71], v[30:31], v[30:31], v[70:71]
	v_pk_add_f32 v[64:65], v[64:65], v[66:67]
	v_pk_add_f32 v[68:69], v[68:69], v[70:71]
	s_nop 0
	v_pk_add_f32 v[64:65], v[64:65], v[68:69]
	s_nop 0
	v_add_f32_e32 v96, v64, v65
	ds_bpermute_b32 v97, v109, v96
	s_waitcnt lgkmcnt(0)
	v_add_f32_e32 v96, v96, v97
	ds_bpermute_b32 v97, v110, v96
	s_waitcnt lgkmcnt(0)
	v_add_f32_e32 v96, v96, v97
	ds_bpermute_b32 v97, v111, v96
	s_waitcnt lgkmcnt(0)
	v_add_f32_e32 v96, v96, v97
	ds_bpermute_b32 v97, v240, v96
	s_waitcnt lgkmcnt(0)
	v_add_f32_e32 v96, v96, v97
	ds_bpermute_b32 v97, v241, v96
	s_waitcnt lgkmcnt(0)
	v_add_f32_e32 v96, v96, v97
	ds_bpermute_b32 v97, v242, v96
	s_waitcnt lgkmcnt(0)
	v_add_f32_e32 v96, v96, v97
	v_fmamk_f32 v98, v96, 0x3a000000, v105
	v_mul_f32_e32 v99, 0x4f800000, v98
	v_cmp_gt_f32_e32 vcc, s17, v98
	s_nop 1
	v_cndmask_b32_e32 v98, v98, v99, vcc
	v_sqrt_f32_e32 v99, v98
	s_nop 0
	v_add_u32_e32 v100, -1, v99
	v_add_u32_e32 v101, 1, v99
	v_fma_f32 v102, -v100, v99, v98
	v_fma_f32 v103, -v101, v99, v98
	v_cmp_ge_f32_e64 s[0:1], 0, v102
	s_nop 1
	v_cndmask_b32_e64 v99, v99, v100, s[0:1]
	v_cmp_lt_f32_e64 s[0:1], 0, v103
	s_nop 1
	v_cndmask_b32_e64 v99, v99, v101, s[0:1]
	v_mul_f32_e32 v100, 0x37800000, v99
	v_cndmask_b32_e32 v99, v99, v100, vcc
	v_cmp_class_f32_e32 vcc, v98, v104
	s_nop 1
	v_cndmask_b32_e32 v98, v99, v98, vcc
	v_div_scale_f32 v99, s[0:1], v98, v98, 1.0
	v_rcp_f32_e32 v101, v99
	v_div_scale_f32 v100, vcc, 1.0, v98, 1.0
	v_fma_f32 v102, -v99, v101, 1.0
	v_fmac_f32_e32 v101, v102, v101
	v_mul_f32_e32 v102, v100, v101
	v_fma_f32 v103, -v99, v102, v100
	v_fmac_f32_e32 v102, v103, v101
	v_fma_f32 v99, -v99, v102, v100
	v_div_fmas_f32 v99, v99, v101, v102
	v_div_fixup_f32 v98, v99, v98, 1.0
	v_pk_mul_f32 v[0:1], v[98:99], v[0:1] op_sel_hi:[0,1]
	v_pk_mul_f32 v[2:3], v[98:99], v[2:3] op_sel_hi:[0,1]
	v_pk_mul_f32 v[4:5], v[98:99], v[4:5] op_sel_hi:[0,1]
	v_pk_mul_f32 v[6:7], v[98:99], v[6:7] op_sel_hi:[0,1]
	v_pk_mul_f32 v[8:9], v[98:99], v[8:9] op_sel_hi:[0,1]
	v_pk_mul_f32 v[10:11], v[98:99], v[10:11] op_sel_hi:[0,1]
	v_pk_mul_f32 v[12:13], v[98:99], v[12:13] op_sel_hi:[0,1]
	v_pk_mul_f32 v[14:15], v[98:99], v[14:15] op_sel_hi:[0,1]
	v_pk_mul_f32 v[16:17], v[98:99], v[16:17] op_sel_hi:[0,1]
	v_pk_mul_f32 v[18:19], v[98:99], v[18:19] op_sel_hi:[0,1]
	v_pk_mul_f32 v[20:21], v[98:99], v[20:21] op_sel_hi:[0,1]
	v_pk_mul_f32 v[22:23], v[98:99], v[22:23] op_sel_hi:[0,1]
	v_pk_mul_f32 v[24:25], v[98:99], v[24:25] op_sel_hi:[0,1]
	v_pk_mul_f32 v[26:27], v[98:99], v[26:27] op_sel_hi:[0,1]
	v_pk_mul_f32 v[28:29], v[98:99], v[28:29] op_sel_hi:[0,1]
	v_pk_mul_f32 v[30:31], v[98:99], v[30:31] op_sel_hi:[0,1]
	v_pk_fma_f32 v[0:1], v[0:1], v[176:177], v[208:209]
	v_pk_fma_f32 v[2:3], v[2:3], v[178:179], v[210:211]
	global_store_dwordx4 v106, v[0:3], s[2:3] nt
	v_pk_fma_f32 v[4:5], v[4:5], v[180:181], v[212:213]
	v_pk_fma_f32 v[6:7], v[6:7], v[182:183], v[214:215]
	global_store_dwordx4 v106, v[4:7], s[2:3] offset:1024 nt
	v_pk_fma_f32 v[8:9], v[8:9], v[184:185], v[216:217]
	v_pk_fma_f32 v[10:11], v[10:11], v[186:187], v[218:219]
	global_store_dwordx4 v106, v[8:11], s[2:3] offset:2048 nt
	v_pk_fma_f32 v[12:13], v[12:13], v[188:189], v[220:221]
	v_pk_fma_f32 v[14:15], v[14:15], v[190:191], v[222:223]
	global_store_dwordx4 v106, v[12:15], s[2:3] offset:3072 nt
	v_pk_fma_f32 v[16:17], v[16:17], v[192:193], v[224:225]
	v_pk_fma_f32 v[18:19], v[18:19], v[194:195], v[226:227]
	global_store_dwordx4 v107, v[16:19], s[2:3] nt
	v_pk_fma_f32 v[20:21], v[20:21], v[196:197], v[228:229]
	v_pk_fma_f32 v[22:23], v[22:23], v[198:199], v[230:231]
	global_store_dwordx4 v107, v[20:23], s[2:3] offset:1024 nt
	v_pk_fma_f32 v[24:25], v[24:25], v[200:201], v[232:233]
	v_pk_fma_f32 v[26:27], v[26:27], v[202:203], v[234:235]
	global_store_dwordx4 v107, v[24:27], s[2:3] offset:2048 nt
	v_pk_fma_f32 v[28:29], v[28:29], v[204:205], v[236:237]
	v_pk_fma_f32 v[30:31], v[30:31], v[206:207], v[238:239]
	global_store_dwordx4 v107, v[28:31], s[2:3] offset:3072 nt
	s_add_u32 s2, s2, s12
	s_addc_u32 s3, s3, s13
	s_add_i32 s16, s16, s28
	s_cmp_lt_i32 s16, 0x8000
	s_cbranch_scc1 .Lp9r_loop
